# v47 + attention epilogue store_o rewritten: 64 per-element exec-masked ladders -> one straight block (in-place 1/l, DPP-fused neighbour product, one even-lane EXEC mask for all 64 LDS stores); forgett
# speedup vs baseline: 1.0024x; 1.0024x over previous
.LBB0_502:
	s_lshl_b32 s0, s25, 13
	v_and_b32_e32 v66, 1, v152
	s_add_i32 s2, s0, 0
	v_cmp_eq_u32_e32 vcc, 0, v66
	v_lshlrev_b32_e32 v66, 10, v155
	v_lshlrev_b32_e32 v67, 1, v154
	v_add3_u32 v66, s2, v66, v67
	s_nop 0
	s_barrier
	v_readlane_b32 s25, v243, 63
	s_nop 1
	v_mov_b32_dpp v67, v50 quad_perm:[1,0,3,2] row_mask:0xf bank_mask:0xf bound_ctrl:1
	v_cvt_pk_bf16_f32 v50, v50, v67
	v_mov_b32_dpp v67, v34 quad_perm:[1,0,3,2] row_mask:0xf bank_mask:0xf bound_ctrl:1
	v_cvt_pk_bf16_f32 v34, v34, v67
	v_mov_b32_dpp v67, v18 quad_perm:[1,0,3,2] row_mask:0xf bank_mask:0xf bound_ctrl:1
	v_cvt_pk_bf16_f32 v18, v18, v67
	v_mov_b32_dpp v67, v2 quad_perm:[1,0,3,2] row_mask:0xf bank_mask:0xf bound_ctrl:1
	v_cvt_pk_bf16_f32 v2, v2, v67
	v_mov_b32_dpp v67, v51 quad_perm:[1,0,3,2] row_mask:0xf bank_mask:0xf bound_ctrl:1
	v_cvt_pk_bf16_f32 v51, v51, v67
	v_mov_b32_dpp v67, v35 quad_perm:[1,0,3,2] row_mask:0xf bank_mask:0xf bound_ctrl:1
	v_cvt_pk_bf16_f32 v35, v35, v67
	v_mov_b32_dpp v67, v19 quad_perm:[1,0,3,2] row_mask:0xf bank_mask:0xf bound_ctrl:1
	v_cvt_pk_bf16_f32 v19, v19, v67
	v_mov_b32_dpp v67, v3 quad_perm:[1,0,3,2] row_mask:0xf bank_mask:0xf bound_ctrl:1
	v_cvt_pk_bf16_f32 v3, v3, v67
	v_mov_b32_dpp v67, v52 quad_perm:[1,0,3,2] row_mask:0xf bank_mask:0xf bound_ctrl:1
	v_cvt_pk_bf16_f32 v52, v52, v67
	v_mov_b32_dpp v67, v36 quad_perm:[1,0,3,2] row_mask:0xf bank_mask:0xf bound_ctrl:1
	v_cvt_pk_bf16_f32 v36, v36, v67
	v_mov_b32_dpp v67, v20 quad_perm:[1,0,3,2] row_mask:0xf bank_mask:0xf bound_ctrl:1
	v_cvt_pk_bf16_f32 v20, v20, v67
	v_mov_b32_dpp v67, v4 quad_perm:[1,0,3,2] row_mask:0xf bank_mask:0xf bound_ctrl:1
	v_cvt_pk_bf16_f32 v4, v4, v67
	v_mov_b32_dpp v67, v53 quad_perm:[1,0,3,2] row_mask:0xf bank_mask:0xf bound_ctrl:1
	v_cvt_pk_bf16_f32 v53, v53, v67
	v_mov_b32_dpp v67, v37 quad_perm:[1,0,3,2] row_mask:0xf bank_mask:0xf bound_ctrl:1
	v_cvt_pk_bf16_f32 v37, v37, v67
	v_mov_b32_dpp v67, v21 quad_perm:[1,0,3,2] row_mask:0xf bank_mask:0xf bound_ctrl:1
	v_cvt_pk_bf16_f32 v21, v21, v67
	v_mov_b32_dpp v67, v5 quad_perm:[1,0,3,2] row_mask:0xf bank_mask:0xf bound_ctrl:1
	v_cvt_pk_bf16_f32 v5, v5, v67
	v_mov_b32_dpp v67, v54 quad_perm:[1,0,3,2] row_mask:0xf bank_mask:0xf bound_ctrl:1
	v_cvt_pk_bf16_f32 v54, v54, v67
	v_mov_b32_dpp v67, v38 quad_perm:[1,0,3,2] row_mask:0xf bank_mask:0xf bound_ctrl:1
	v_cvt_pk_bf16_f32 v38, v38, v67
	v_mov_b32_dpp v67, v22 quad_perm:[1,0,3,2] row_mask:0xf bank_mask:0xf bound_ctrl:1
	v_cvt_pk_bf16_f32 v22, v22, v67
	v_mov_b32_dpp v67, v6 quad_perm:[1,0,3,2] row_mask:0xf bank_mask:0xf bound_ctrl:1
	v_cvt_pk_bf16_f32 v6, v6, v67
	v_mov_b32_dpp v67, v55 quad_perm:[1,0,3,2] row_mask:0xf bank_mask:0xf bound_ctrl:1
	v_cvt_pk_bf16_f32 v55, v55, v67
	v_mov_b32_dpp v67, v39 quad_perm:[1,0,3,2] row_mask:0xf bank_mask:0xf bound_ctrl:1
	v_cvt_pk_bf16_f32 v39, v39, v67
	v_mov_b32_dpp v67, v23 quad_perm:[1,0,3,2] row_mask:0xf bank_mask:0xf bound_ctrl:1
	v_cvt_pk_bf16_f32 v23, v23, v67
	v_mov_b32_dpp v67, v7 quad_perm:[1,0,3,2] row_mask:0xf bank_mask:0xf bound_ctrl:1
	v_cvt_pk_bf16_f32 v7, v7, v67
	v_mov_b32_dpp v67, v56 quad_perm:[1,0,3,2] row_mask:0xf bank_mask:0xf bound_ctrl:1
	v_cvt_pk_bf16_f32 v56, v56, v67
	v_mov_b32_dpp v67, v40 quad_perm:[1,0,3,2] row_mask:0xf bank_mask:0xf bound_ctrl:1
	v_cvt_pk_bf16_f32 v40, v40, v67
	v_mov_b32_dpp v67, v24 quad_perm:[1,0,3,2] row_mask:0xf bank_mask:0xf bound_ctrl:1
	v_cvt_pk_bf16_f32 v24, v24, v67
	v_mov_b32_dpp v67, v8 quad_perm:[1,0,3,2] row_mask:0xf bank_mask:0xf bound_ctrl:1
	v_cvt_pk_bf16_f32 v8, v8, v67
	v_mov_b32_dpp v67, v57 quad_perm:[1,0,3,2] row_mask:0xf bank_mask:0xf bound_ctrl:1
	v_cvt_pk_bf16_f32 v57, v57, v67
	v_mov_b32_dpp v67, v41 quad_perm:[1,0,3,2] row_mask:0xf bank_mask:0xf bound_ctrl:1
	v_cvt_pk_bf16_f32 v41, v41, v67
	v_mov_b32_dpp v67, v25 quad_perm:[1,0,3,2] row_mask:0xf bank_mask:0xf bound_ctrl:1
	v_cvt_pk_bf16_f32 v25, v25, v67
	v_mov_b32_dpp v67, v9 quad_perm:[1,0,3,2] row_mask:0xf bank_mask:0xf bound_ctrl:1
	v_cvt_pk_bf16_f32 v9, v9, v67
	v_mov_b32_dpp v67, v58 quad_perm:[1,0,3,2] row_mask:0xf bank_mask:0xf bound_ctrl:1
	v_cvt_pk_bf16_f32 v58, v58, v67
	v_mov_b32_dpp v67, v42 quad_perm:[1,0,3,2] row_mask:0xf bank_mask:0xf bound_ctrl:1
	v_cvt_pk_bf16_f32 v42, v42, v67
	v_mov_b32_dpp v67, v26 quad_perm:[1,0,3,2] row_mask:0xf bank_mask:0xf bound_ctrl:1
	v_cvt_pk_bf16_f32 v26, v26, v67
	v_mov_b32_dpp v67, v10 quad_perm:[1,0,3,2] row_mask:0xf bank_mask:0xf bound_ctrl:1
	v_cvt_pk_bf16_f32 v10, v10, v67
	v_mov_b32_dpp v67, v59 quad_perm:[1,0,3,2] row_mask:0xf bank_mask:0xf bound_ctrl:1
	v_cvt_pk_bf16_f32 v59, v59, v67
	v_mov_b32_dpp v67, v43 quad_perm:[1,0,3,2] row_mask:0xf bank_mask:0xf bound_ctrl:1
	v_cvt_pk_bf16_f32 v43, v43, v67
	v_mov_b32_dpp v67, v27 quad_perm:[1,0,3,2] row_mask:0xf bank_mask:0xf bound_ctrl:1
	v_cvt_pk_bf16_f32 v27, v27, v67
	v_mov_b32_dpp v67, v11 quad_perm:[1,0,3,2] row_mask:0xf bank_mask:0xf bound_ctrl:1
	v_cvt_pk_bf16_f32 v11, v11, v67
	v_mov_b32_dpp v67, v60 quad_perm:[1,0,3,2] row_mask:0xf bank_mask:0xf bound_ctrl:1
	v_cvt_pk_bf16_f32 v60, v60, v67
	v_mov_b32_dpp v67, v44 quad_perm:[1,0,3,2] row_mask:0xf bank_mask:0xf bound_ctrl:1
	v_cvt_pk_bf16_f32 v44, v44, v67
	v_mov_b32_dpp v67, v28 quad_perm:[1,0,3,2] row_mask:0xf bank_mask:0xf bound_ctrl:1
	v_cvt_pk_bf16_f32 v28, v28, v67
	v_mov_b32_dpp v67, v12 quad_perm:[1,0,3,2] row_mask:0xf bank_mask:0xf bound_ctrl:1
	v_cvt_pk_bf16_f32 v12, v12, v67
	v_mov_b32_dpp v67, v61 quad_perm:[1,0,3,2] row_mask:0xf bank_mask:0xf bound_ctrl:1
	v_cvt_pk_bf16_f32 v61, v61, v67
	v_mov_b32_dpp v67, v45 quad_perm:[1,0,3,2] row_mask:0xf bank_mask:0xf bound_ctrl:1
	v_cvt_pk_bf16_f32 v45, v45, v67
	v_mov_b32_dpp v67, v29 quad_perm:[1,0,3,2] row_mask:0xf bank_mask:0xf bound_ctrl:1
	v_cvt_pk_bf16_f32 v29, v29, v67
	v_mov_b32_dpp v67, v13 quad_perm:[1,0,3,2] row_mask:0xf bank_mask:0xf bound_ctrl:1
	v_cvt_pk_bf16_f32 v13, v13, v67
	v_mov_b32_dpp v67, v62 quad_perm:[1,0,3,2] row_mask:0xf bank_mask:0xf bound_ctrl:1
	v_cvt_pk_bf16_f32 v62, v62, v67
	v_mov_b32_dpp v67, v46 quad_perm:[1,0,3,2] row_mask:0xf bank_mask:0xf bound_ctrl:1
	v_cvt_pk_bf16_f32 v46, v46, v67
	v_mov_b32_dpp v67, v30 quad_perm:[1,0,3,2] row_mask:0xf bank_mask:0xf bound_ctrl:1
	v_cvt_pk_bf16_f32 v30, v30, v67
	v_mov_b32_dpp v67, v14 quad_perm:[1,0,3,2] row_mask:0xf bank_mask:0xf bound_ctrl:1
	v_cvt_pk_bf16_f32 v14, v14, v67
	v_mov_b32_dpp v67, v63 quad_perm:[1,0,3,2] row_mask:0xf bank_mask:0xf bound_ctrl:1
	v_cvt_pk_bf16_f32 v63, v63, v67
	v_mov_b32_dpp v67, v47 quad_perm:[1,0,3,2] row_mask:0xf bank_mask:0xf bound_ctrl:1
	v_cvt_pk_bf16_f32 v47, v47, v67
	v_mov_b32_dpp v67, v31 quad_perm:[1,0,3,2] row_mask:0xf bank_mask:0xf bound_ctrl:1
	v_cvt_pk_bf16_f32 v31, v31, v67
	v_mov_b32_dpp v67, v15 quad_perm:[1,0,3,2] row_mask:0xf bank_mask:0xf bound_ctrl:1
	v_cvt_pk_bf16_f32 v15, v15, v67
	v_mov_b32_dpp v67, v64 quad_perm:[1,0,3,2] row_mask:0xf bank_mask:0xf bound_ctrl:1
	v_cvt_pk_bf16_f32 v64, v64, v67
	v_mov_b32_dpp v67, v48 quad_perm:[1,0,3,2] row_mask:0xf bank_mask:0xf bound_ctrl:1
	v_cvt_pk_bf16_f32 v48, v48, v67
	v_mov_b32_dpp v67, v32 quad_perm:[1,0,3,2] row_mask:0xf bank_mask:0xf bound_ctrl:1
	v_cvt_pk_bf16_f32 v32, v32, v67
	v_mov_b32_dpp v67, v16 quad_perm:[1,0,3,2] row_mask:0xf bank_mask:0xf bound_ctrl:1
	v_cvt_pk_bf16_f32 v16, v16, v67
	v_mov_b32_dpp v67, v65 quad_perm:[1,0,3,2] row_mask:0xf bank_mask:0xf bound_ctrl:1
	v_cvt_pk_bf16_f32 v65, v65, v67
	v_mov_b32_dpp v67, v49 quad_perm:[1,0,3,2] row_mask:0xf bank_mask:0xf bound_ctrl:1
	v_cvt_pk_bf16_f32 v49, v49, v67
	v_mov_b32_dpp v67, v33 quad_perm:[1,0,3,2] row_mask:0xf bank_mask:0xf bound_ctrl:1
	v_cvt_pk_bf16_f32 v33, v33, v67
	v_mov_b32_dpp v67, v17 quad_perm:[1,0,3,2] row_mask:0xf bank_mask:0xf bound_ctrl:1
	v_cvt_pk_bf16_f32 v17, v17, v67
	s_and_saveexec_b64 s[0:1], vcc
	ds_write_b32 v66, v50
	ds_write_b32 v66, v34 offset:64
	ds_write_b32 v66, v18 offset:128
	ds_write_b32 v66, v2 offset:192
	ds_write_b32 v66, v51 offset:256
	ds_write_b32 v66, v35 offset:320
	ds_write_b32 v66, v19 offset:384
	ds_write_b32 v66, v3 offset:448
	ds_write_b32 v66, v52 offset:512
	ds_write_b32 v66, v36 offset:576
	ds_write_b32 v66, v20 offset:640
	ds_write_b32 v66, v4 offset:704
	ds_write_b32 v66, v53 offset:768
	ds_write_b32 v66, v37 offset:832
	ds_write_b32 v66, v21 offset:896
	ds_write_b32 v66, v5 offset:960
	ds_write_b32 v66, v54 offset:2048
	ds_write_b32 v66, v38 offset:2112
	ds_write_b32 v66, v22 offset:2176
	ds_write_b32 v66, v6 offset:2240
	ds_write_b32 v66, v55 offset:2304
	ds_write_b32 v66, v39 offset:2368
	ds_write_b32 v66, v23 offset:2432
	ds_write_b32 v66, v7 offset:2496
	ds_write_b32 v66, v56 offset:2560
	ds_write_b32 v66, v40 offset:2624
	ds_write_b32 v66, v24 offset:2688
	ds_write_b32 v66, v8 offset:2752
	ds_write_b32 v66, v57 offset:2816
	ds_write_b32 v66, v41 offset:2880
	ds_write_b32 v66, v25 offset:2944
	ds_write_b32 v66, v9 offset:3008
	ds_write_b32 v66, v58 offset:4096
	ds_write_b32 v66, v42 offset:4160
	ds_write_b32 v66, v26 offset:4224
	ds_write_b32 v66, v10 offset:4288
	ds_write_b32 v66, v59 offset:4352
	ds_write_b32 v66, v43 offset:4416
	ds_write_b32 v66, v27 offset:4480
	ds_write_b32 v66, v11 offset:4544
	ds_write_b32 v66, v60 offset:4608
	ds_write_b32 v66, v44 offset:4672
	ds_write_b32 v66, v28 offset:4736
	ds_write_b32 v66, v12 offset:4800
	ds_write_b32 v66, v61 offset:4864
	ds_write_b32 v66, v45 offset:4928
	ds_write_b32 v66, v29 offset:4992
	ds_write_b32 v66, v13 offset:5056
	ds_write_b32 v66, v62 offset:6144
	ds_write_b32 v66, v46 offset:6208
	ds_write_b32 v66, v30 offset:6272
	ds_write_b32 v66, v14 offset:6336
	ds_write_b32 v66, v63 offset:6400
	ds_write_b32 v66, v47 offset:6464
	ds_write_b32 v66, v31 offset:6528
	ds_write_b32 v66, v15 offset:6592
	ds_write_b32 v66, v64 offset:6656
	ds_write_b32 v66, v48 offset:6720
	ds_write_b32 v66, v32 offset:6784
	ds_write_b32 v66, v16 offset:6848
	ds_write_b32 v66, v65 offset:6912
	ds_write_b32 v66, v49 offset:6976
	ds_write_b32 v66, v33 offset:7040
	ds_write_b32 v66, v17 offset:7104
	s_or_b64 exec, exec, s[0:1]
	s_lshl_b64 s[0:1], s[4:5], 12
	v_readlane_b32 s4, v245, 30
	v_readlane_b32 s5, v245, 31
	s_add_u32 s0, s4, s0
	v_lshlrev_b32_e32 v2, 4, v152
	s_addc_u32 s1, s5, s1
	v_and_b32_e32 v162, 0xf0, v2
	s_add_u32 s3, s0, s34
	v_lshrrev_b32_e32 v10, 4, v153
	v_add_u32_e32 v11, s2, v162
	s_addc_u32 s4, s1, s35
	s_ashr_i32 s29, s28, 31
	s_waitcnt lgkmcnt(0)
	v_lshl_add_u32 v2, v10, 8, v11
	s_lshl_b64 s[0:1], s[28:29], 12
	ds_read_b128 v[2:5], v2
	s_add_u32 s0, s3, s0
	s_addc_u32 s1, s4, s1
	v_lshl_add_u64 v[6:7], s[0:1], 0, v[162:163]
	v_lshlrev_b32_e32 v162, 12, v10
	v_lshl_add_u64 v[8:9], v[6:7], 0, v[162:163]
	s_waitcnt lgkmcnt(0)
	global_store_dwordx4 v[8:9], v[2:5], off offset:1024
	v_or_b32_e32 v8, 4, v10
	v_lshlrev_b32_e32 v162, 12, v8
	v_lshl_add_u32 v2, v8, 8, v11
	ds_read_b128 v[2:5], v2
	v_lshl_add_u64 v[8:9], v[6:7], 0, v[162:163]
	s_waitcnt lgkmcnt(0)
	global_store_dwordx4 v[8:9], v[2:5], off offset:1024
	v_or_b32_e32 v8, 8, v10
	s_nop 0
	v_lshl_add_u32 v2, v8, 8, v11
	ds_read_b128 v[2:5], v2
	v_lshlrev_b32_e32 v162, 12, v8
	v_lshl_add_u64 v[8:9], v[6:7], 0, v[162:163]
	s_waitcnt lgkmcnt(0)
	global_store_dwordx4 v[8:9], v[2:5], off offset:1024
	v_or_b32_e32 v8, 12, v10
	s_nop 0
	v_lshl_add_u32 v2, v8, 8, v11
	ds_read_b128 v[2:5], v2
	v_lshlrev_b32_e32 v162, 12, v8
	v_lshl_add_u64 v[8:9], v[6:7], 0, v[162:163]
	s_waitcnt lgkmcnt(0)
	global_store_dwordx4 v[8:9], v[2:5], off offset:1024
	v_or_b32_e32 v8, 16, v10
	s_nop 0
	v_lshl_add_u32 v2, v8, 8, v11
	ds_read_b128 v[2:5], v2
	v_lshlrev_b32_e32 v162, 12, v8
	v_lshl_add_u64 v[8:9], v[6:7], 0, v[162:163]
	s_waitcnt lgkmcnt(0)
	global_store_dwordx4 v[8:9], v[2:5], off offset:1024
	v_or_b32_e32 v8, 20, v10
	s_nop 0
	v_lshl_add_u32 v2, v8, 8, v11
	ds_read_b128 v[2:5], v2
	v_lshlrev_b32_e32 v162, 12, v8
	v_lshl_add_u64 v[8:9], v[6:7], 0, v[162:163]
	s_waitcnt lgkmcnt(0)
	global_store_dwordx4 v[8:9], v[2:5], off offset:1024
	v_or_b32_e32 v8, 24, v10
	s_nop 0
	v_lshl_add_u32 v2, v8, 8, v11
	ds_read_b128 v[2:5], v2
	v_lshlrev_b32_e32 v162, 12, v8
	v_lshl_add_u64 v[8:9], v[6:7], 0, v[162:163]
	s_waitcnt lgkmcnt(0)
	global_store_dwordx4 v[8:9], v[2:5], off offset:1024
	v_or_b32_e32 v8, 28, v10
	s_nop 0
	v_lshl_add_u32 v2, v8, 8, v11
	ds_read_b128 v[2:5], v2
	v_lshlrev_b32_e32 v162, 12, v8
	v_lshl_add_u64 v[6:7], v[6:7], 0, v[162:163]
	s_waitcnt lgkmcnt(0)
	global_store_dwordx4 v[6:7], v[2:5], off offset:1024
	s_barrier
	s_and_saveexec_b64 s[0:1], s[36:37]
	s_cbranch_execnz .LBB0_479
	s_branch .LBB0_480

.LBB0_639:
	s_or_b64 exec, exec, s[0:1]
	s_abs_i32 s0, s13
	v_readlane_b32 s1, v243, 0
	s_mul_hi_u32 s1, s0, s1
	v_readlane_b32 s4, v243, 53
	s_mul_i32 s2, s1, s4
	s_sub_i32 s0, s0, s2
	s_ashr_i32 s8, s13, 31
	s_add_i32 s2, s1, 1
	s_sub_i32 s3, s0, s4
	s_cmp_ge_u32 s0, s4
	s_cselect_b32 s1, s2, s1
	s_cselect_b32 s0, s3, s0
	s_add_i32 s2, s1, 1
	s_cmp_ge_u32 s0, s4
	s_cselect_b32 s0, s2, s1
	s_xor_b32 s11, s0, s8
	s_sub_i32 s9, s11, s8
	s_mul_i32 s0, s9, s4
	s_sub_i32 s0, s13, s0
	v_readlane_b32 s1, v243, 54
	s_add_i32 s0, s0, s1
	s_ashr_i32 s1, s0, 31
	s_lshl_b64 s[2:3], s[0:1], 13
	v_readlane_b32 s4, v245, 11
	v_mov_b32_e32 v180, v0
	v_readlane_b32 s5, v245, 12
	s_add_u32 s2, s4, s2
	s_addc_u32 s3, s5, s3
	v_lshlrev_b32_e32 v6, 2, v180
	v_ashrrev_i32_e32 v7, 31, v6
	v_lshl_add_u64 v[2:3], v[6:7], 2, s[2:3]
	global_load_dwordx4 v[2:5], v[2:3], off
	v_and_b32_e32 v7, 64, v176
	v_add_u32_e32 v1, -1, v176
	v_cmp_lt_i32_e32 vcc, v1, v7
	v_and_b32_e32 v169, 63, v180
	v_add_u32_e32 v8, -2, v176
	v_cndmask_b32_e32 v1, v1, v176, vcc
	v_lshlrev_b32_e32 v1, 2, v1
	v_cmp_eq_u32_e32 vcc, 0, v169
	v_readfirstlane_b32 s13, v180
	s_ashr_i32 s5, s13, 6
	s_waitcnt vmcnt(0)
	v_add_f32_e32 v3, v2, v3
	v_add_f32_e32 v4, v4, v3
	v_add_f32_e32 v5, v5, v4
	ds_bpermute_b32 v1, v1, v5
	s_waitcnt lgkmcnt(0)
	v_add_f32_e32 v1, v5, v1
	v_cndmask_b32_e32 v1, v1, v5, vcc
	v_cmp_lt_i32_e32 vcc, v8, v7
	s_nop 1
	v_cndmask_b32_e32 v8, v8, v176, vcc
	v_lshlrev_b32_e32 v8, 2, v8
	ds_bpermute_b32 v8, v8, v1
	v_cmp_gt_u32_e32 vcc, 2, v169
	s_waitcnt lgkmcnt(0)
	v_add_f32_e32 v8, v1, v8
	v_cndmask_b32_e32 v1, v8, v1, vcc
	v_add_u32_e32 v8, -4, v176
	v_cmp_lt_i32_e32 vcc, v8, v7
	s_nop 1
	v_cndmask_b32_e32 v8, v8, v176, vcc
	v_lshlrev_b32_e32 v8, 2, v8
	ds_bpermute_b32 v8, v8, v1
	v_cmp_gt_u32_e32 vcc, 4, v169
	s_waitcnt lgkmcnt(0)
	v_add_f32_e32 v8, v1, v8
	v_cndmask_b32_e32 v1, v8, v1, vcc
	v_add_u32_e32 v8, -8, v176
	v_cmp_lt_i32_e32 vcc, v8, v7
	s_nop 1
	v_cndmask_b32_e32 v8, v8, v176, vcc
	v_lshlrev_b32_e32 v8, 2, v8
	ds_bpermute_b32 v8, v8, v1
	v_cmp_gt_u32_e32 vcc, 8, v169
	s_waitcnt lgkmcnt(0)
	v_add_f32_e32 v8, v1, v8
	v_cndmask_b32_e32 v1, v8, v1, vcc
	v_add_u32_e32 v8, -16, v176
	v_cmp_lt_i32_e32 vcc, v8, v7
	s_nop 1
	v_cndmask_b32_e32 v8, v8, v176, vcc
	v_lshlrev_b32_e32 v8, 2, v8
	ds_bpermute_b32 v8, v8, v1
	v_cmp_gt_u32_e32 vcc, 16, v169
	s_waitcnt lgkmcnt(0)
	v_add_f32_e32 v8, v1, v8
	v_cndmask_b32_e32 v1, v8, v1, vcc
	v_subrev_u32_e32 v8, 32, v176
	v_cmp_lt_i32_e32 vcc, v8, v7
	s_nop 1
	v_cndmask_b32_e32 v7, v8, v176, vcc
	v_lshlrev_b32_e32 v7, 2, v7
	ds_bpermute_b32 v7, v7, v1
	v_cmp_eq_u32_e32 vcc, 63, v169
	s_waitcnt lgkmcnt(0)
	v_add_f32_e32 v7, v1, v7
	s_and_saveexec_b64 s[2:3], vcc
	s_lshl_b32 s1, s5, 2
	s_add_i32 s1, s1, 0
	s_add_i32 s1, s1, 0x12840
	v_mov_b32_e32 v8, s1
	ds_write_b32 v8, v7
	s_or_b64 exec, exec, s[2:3]
	s_mul_hi_i32 s1, s0, 0x2aaaaaab
	s_lshr_b32 s2, s1, 31
	s_add_i32 s18, s1, s2
	s_lshl_b32 s2, s9, 8
	s_mul_i32 s1, s18, 6
	s_ashr_i32 s19, s18, 31
	s_sub_i32 s2, 0x700, s2
	s_sub_i32 s3, s0, s1
	s_lshl_b64 s[0:1], s[18:19], 11
	s_ashr_i32 s4, s2, 31
	s_add_u32 s96, s0, s2
	s_addc_u32 s97, s1, s4
	s_mul_i32 s0, s97, 0x3000
	s_mul_hi_u32 s1, s96, 0x3000
	s_add_i32 s1, s1, s0
	s_mul_i32 s0, s96, 0x3000
	v_readlane_b32 s20, v245, 14
	s_add_u32 s4, s20, s0
	v_readlane_b32 s21, v245, 15
	s_addc_u32 s19, s21, s1
	s_lshl_b32 s0, s3, 7
	s_ashr_i32 s1, s0, 31
	s_lshl_b64 s[34:35], s[0:1], 1
	s_add_u32 s0, s4, s34
	s_addc_u32 s1, s19, s35
	s_add_u32 s0, s0, 0x1e00
	s_addc_u32 s1, s1, 0
	s_mul_i32 s4, s18, 0x1800000
	s_mul_hi_i32 s3, s18, 0x1800000
	s_add_u32 s4, s20, s4
	s_addc_u32 s3, s21, s3
	s_add_u32 s4, s4, s34
	s_addc_u32 s3, s3, s35
	s_add_u32 s22, s4, 0x2400
	s_addc_u32 s23, s3, 0
	s_add_u32 s28, s4, 0x2a00
	s_addc_u32 s29, s3, 0
	v_lshlrev_b32_e32 v22, 3, v180
	v_cmp_gt_u32_e64 s[38:39], 32, v169
	s_add_i32 s3, 0, 0x12840
	v_and_b32_e32 v8, 0x78, v22
	v_cndmask_b32_e64 v1, v7, v1, s[38:39]
	v_mov_b32_e32 v7, s3
	v_lshlrev_b32_e32 v50, 1, v8
	s_waitcnt lgkmcnt(0)
	s_barrier
	ds_read_b128 v[8:11], v7
	s_ashr_i32 s3, s2, 8
	v_readlane_b32 s4, v243, 56
	s_cmp_gt_i32 s5, 0
	s_cselect_b64 vcc, -1, 0
	v_mov_b32_e32 v7, s4
	ds_read_b128 v[12:15], v7
	s_waitcnt lgkmcnt(1)
	v_add_f32_e32 v7, 0, v8
	s_cmp_gt_i32 s3, -1
	v_cndmask_b32_e32 v8, 0, v7, vcc
	s_cselect_b64 vcc, -1, 0
	s_cmp_gt_i32 s5, 1
	v_cndmask_b32_e32 v7, 0, v7, vcc
	v_add_f32_e32 v16, v9, v8
	s_cselect_b64 vcc, -1, 0
	s_cmp_lt_i32 s3, 1
	v_cndmask_b32_e32 v8, v8, v16, vcc
	v_add_f32_e32 v9, v9, v7
	s_cselect_b64 vcc, -1, 0
	s_cmp_gt_i32 s5, 2
	v_cndmask_b32_e32 v7, v9, v7, vcc
	v_add_f32_e32 v9, v10, v8
	s_cselect_b64 vcc, -1, 0
	s_cmp_lt_i32 s3, 2
	v_cndmask_b32_e32 v8, v8, v9, vcc
	v_add_f32_e32 v9, v10, v7
	s_cselect_b64 vcc, -1, 0
	s_cmp_gt_i32 s5, 3
	v_cndmask_b32_e32 v7, v9, v7, vcc
	v_add_f32_e32 v9, v11, v8
	s_cselect_b64 vcc, -1, 0
	s_cmp_lt_i32 s3, 3
	v_cndmask_b32_e32 v8, v8, v9, vcc
	v_add_f32_e32 v9, v11, v7
	s_cselect_b64 vcc, -1, 0
	s_cmp_gt_i32 s5, 4
	v_cndmask_b32_e32 v7, v9, v7, vcc
	s_waitcnt lgkmcnt(0)
	v_add_f32_e32 v9, v12, v8
	s_cselect_b64 vcc, -1, 0
	s_cmp_lt_i32 s3, 4
	v_cndmask_b32_e32 v8, v8, v9, vcc
	v_add_f32_e32 v9, v12, v7
	s_cselect_b64 vcc, -1, 0
	s_cmp_gt_i32 s5, 5
	v_cndmask_b32_e32 v7, v9, v7, vcc
	v_add_f32_e32 v9, v13, v8
	s_cselect_b64 vcc, -1, 0
	s_cmp_lt_i32 s3, 5
	v_cndmask_b32_e32 v8, v8, v9, vcc
	v_add_f32_e32 v9, v13, v7
	s_cselect_b64 vcc, -1, 0
	s_cmp_gt_i32 s5, 6
	v_cndmask_b32_e32 v7, v9, v7, vcc
	v_add_f32_e32 v9, v14, v8
	s_cselect_b64 vcc, -1, 0
	s_cmp_lt_i32 s3, 6
	v_cndmask_b32_e32 v8, v8, v9, vcc
	v_add_f32_e32 v9, v14, v7
	s_cselect_b64 vcc, -1, 0
	s_cmp_gt_i32 s5, 7
	v_cndmask_b32_e32 v7, v9, v7, vcc
	v_add_f32_e32 v9, v15, v8
	s_cselect_b64 vcc, -1, 0
	s_cmp_lt_i32 s3, 7
	v_cndmask_b32_e32 v8, v8, v9, vcc
	v_add_f32_e32 v9, v15, v7
	s_cselect_b64 vcc, -1, 0
	v_sub_f32_e32 v1, v1, v5
	v_cndmask_b32_e32 v7, v9, v7, vcc
	v_add_f32_e32 v1, v1, v8
	v_sub_f32_e32 v8, v1, v7
	v_ashrrev_i32_e32 v192, 4, v180
	v_add_f32 v2, v2, v8
	v_add_f32 v3, v3, v8
	v_add_f32 v4, v4, v8
	v_add_f32 v5, v5, v8
	s_mov_b32 s4, 0x3fb8aa3b
	v_readlane_b32 s3, v243, 57
	v_add_u32_e32 v23, 32, v192
	v_mul_f32 v4, v4, s4
	v_mul_f32 v5, v5, s4
	v_mul_f32 v2, v2, s4
	v_mul_f32 v3, v3, s4
	v_lshl_add_u32 v1, v6, 2, s3
	v_mov_b64_e32 v[18:19], s[28:29]
	v_mov_b64_e32 v[20:21], s[22:23]
	ds_write_b128 v1, v[2:5]
	v_mad_i64_i32 v[2:3], s[18:19], v192, s33, v[18:19]
	v_mov_b32_e32 v51, v163
	v_mad_i64_i32 v[6:7], s[18:19], v192, s33, v[20:21]
	v_mad_i64_i32 v[8:9], s[18:19], v23, s33, v[20:21]
	v_lshl_add_u64 v[2:3], v[2:3], 0, v[50:51]
	v_lshl_add_u64 v[6:7], v[6:7], 0, v[50:51]
	v_lshl_add_u64 v[10:11], v[8:9], 0, v[50:51]
	s_waitcnt lgkmcnt(0)
	s_barrier
	global_load_dwordx4 v[2:5], v[2:3], off
	s_nop 0
	global_load_dwordx4 v[6:9], v[6:7], off
	s_nop 0
	global_load_dwordx4 v[10:13], v[10:11], off
	v_mad_i64_i32 v[14:15], s[18:19], v23, s33, v[18:19]
	v_lshl_add_u64 v[14:15], v[14:15], 0, v[50:51]
	global_load_dwordx4 v[14:17], v[14:15], off
	v_and_b32_e32 v1, 0xfffff0, v192
	v_lshlrev_b32_e32 v24, 1, v192
	v_and_or_b32 v1, v24, 8, v1
	v_lshrrev_b32_e32 v24, 1, v192
	v_and_b32_e32 v25, 3, v192
	v_and_or_b32 v24, v24, 4, v25
	v_and_b32_e32 v25, 0xfffff0, v23
	v_lshlrev_b32_e32 v23, 1, v23
	v_and_or_b32 v23, v23, 8, v25
	v_lshrrev_b32_e32 v1, 1, v1
	v_bfe_u32 v22, v22, 5, 2
	v_lshrrev_b32_e32 v23, 1, v23
	v_or_b32_e32 v1, v1, v22
	v_or_b32_e32 v22, v23, v22
	v_lshlrev_b32_e32 v23, 8, v192
	v_and_b32_e32 v25, 0x70, v180
	v_lshlrev_b32_e32 v1, 9, v1
	v_lshlrev_b32_e32 v24, 6, v24
	v_lshlrev_b32_e32 v22, 9, v22
	v_bitop3_b32 v25, v50, v23, v25 bitop3:0xde
	v_and_b32_e32 v182, 31, v180
	v_and_b32_e32 v23, 48, v50
	s_lshl_b32 s4, s5, 5
	v_lshrrev_b32_e32 v181, 5, v169
	v_or3_b32 v1, v1, v24, v23
	v_or3_b32 v24, v22, v24, v23
	v_or_b32_e32 v26, s4, v182
	v_mov_b64_e32 v[22:23], s[0:1]
	v_mad_i64_i32 v[22:23], s[0:1], v26, s33, v[22:23]
	v_lshlrev_b32_e32 v162, 4, v181
	v_lshl_add_u64 v[22:23], v[22:23], 0, v[162:163]
	global_load_dwordx4 v[142:145], v[22:23], off
	global_load_dwordx4 v[138:141], v[22:23], off offset:32
	global_load_dwordx4 v[134:137], v[22:23], off offset:64
	global_load_dwordx4 v[130:133], v[22:23], off offset:96
	global_load_dwordx4 v[126:129], v[22:23], off offset:128
	global_load_dwordx4 v[122:125], v[22:23], off offset:160
	global_load_dwordx4 v[118:121], v[22:23], off offset:192
	global_load_dwordx4 v[114:117], v[22:23], off offset:224
	v_add_u32_e32 v193, 0, v25
	v_add_u32_e32 v194, 0, v1
	v_add_u32_e32 v1, 64, v192
	s_waitcnt vmcnt(10)
	ds_write_b128 v193, v[6:9] offset:32768
	s_waitcnt vmcnt(9)
	ds_write_b128 v193, v[10:13] offset:40960
	ds_write_b128 v194, v[2:5]
	v_mad_i64_i32 v[2:3], s[0:1], v1, s33, v[18:19]
	v_add_u32_e32 v6, 0x60, v192
	v_add_u32_e32 v195, 0, v24
	v_lshl_add_u64 v[2:3], v[2:3], 0, v[50:51]
	v_mad_i64_i32 v[4:5], s[0:1], v6, s33, v[18:19]
	s_waitcnt vmcnt(8)
	ds_write_b128 v195, v[14:17]
	s_waitcnt lgkmcnt(0)
	s_barrier
	v_lshl_add_u64 v[4:5], v[4:5], 0, v[50:51]
	global_load_dwordx4 v[38:41], v[2:3], off
	global_load_dwordx4 v[34:37], v[4:5], off
	v_mad_i64_i32 v[2:3], s[0:1], v1, s33, v[20:21]
	v_lshl_add_u64 v[2:3], v[2:3], 0, v[50:51]
	v_mad_i64_i32 v[4:5], s[0:1], v6, s33, v[20:21]
	v_lshl_add_u64 v[4:5], v[4:5], 0, v[50:51]
	global_load_dwordx4 v[46:49], v[2:3], off
	global_load_dwordx4 v[42:45], v[4:5], off
	v_lshlrev_b32_e32 v186, 2, v181
	v_sub_u32_e32 v1, v182, v186
	v_lshlrev_b32_e32 v179, 4, v180
	s_movk_i32 s0, 0x70
	v_and_b32_e32 v2, 0x70, v179
	v_lshl_add_u32 v3, v182, 8, 0
	v_bitop3_b32 v4, v162, v179, s0 bitop3:0x78
	v_add_u32_e32 v191, v3, v4
	v_bitop3_b32 v4, v162, v2, 32 bitop3:0x36
	s_movk_i32 s0, 0x60
	v_add_u32_e32 v190, v3, v4
	v_bitop3_b32 v4, v162, v2, 64 bitop3:0x36
	v_bitop3_b32 v2, v162, v2, s0 bitop3:0x36
	v_add_u32_e32 v189, v3, v4
	v_add_u32_e32 v188, v3, v2
	ds_read_b128 v[2:5], v191 offset:32768
	ds_read_b128 v[6:9], v191 offset:40960
	s_waitcnt vmcnt(11) lgkmcnt(1)
	v_mfma_f32_32x32x16_bf16 v[18:33], v[2:5], v[142:145], 0
	ds_read_b128 v[52:55], v190 offset:32768
	ds_read_b128 v[56:59], v190 offset:40960
	v_add_u32_e32 v51, s3, v162
	s_add_i32 s27, s4, s2
	v_add_u32_e32 v187, s27, v1
	s_cmp_gt_i32 s27, 62
	s_waitcnt lgkmcnt(2)
	v_mfma_f32_32x32x16_bf16 v[2:17], v[6:9], v[142:145], 0
	s_waitcnt vmcnt(10) lgkmcnt(1)
	v_mfma_f32_32x32x16_bf16 v[18:33], v[52:55], v[138:141], v[18:33]
	s_waitcnt lgkmcnt(0)
	v_mfma_f32_32x32x16_bf16 v[2:17], v[56:59], v[138:141], v[2:17]
	ds_read_b128 v[52:55], v189 offset:32768
	ds_read_b128 v[56:59], v189 offset:40960
	s_waitcnt vmcnt(9) lgkmcnt(1)
	v_mfma_f32_32x32x16_bf16 v[18:33], v[52:55], v[134:137], v[18:33]
	s_waitcnt lgkmcnt(0)
	v_mfma_f32_32x32x16_bf16 v[2:17], v[56:59], v[134:137], v[2:17]
	ds_read_b128 v[52:55], v188 offset:32768
	ds_read_b128 v[56:59], v188 offset:40960
	s_waitcnt vmcnt(8) lgkmcnt(1)
	v_mfma_f32_32x32x16_bf16 v[18:33], v[52:55], v[130:133], v[18:33]
	s_waitcnt lgkmcnt(0)
	v_mfma_f32_32x32x16_bf16 v[2:17], v[56:59], v[130:133], v[2:17]
	ds_read_b128 v[52:55], v191 offset:32896
	ds_read_b128 v[56:59], v191 offset:41088
	s_waitcnt vmcnt(7) lgkmcnt(1)
	v_mfma_f32_32x32x16_bf16 v[18:33], v[52:55], v[126:129], v[18:33]
	s_waitcnt lgkmcnt(0)
	v_mfma_f32_32x32x16_bf16 v[2:17], v[56:59], v[126:129], v[2:17]
	ds_read_b128 v[52:55], v190 offset:32896
	ds_read_b128 v[56:59], v190 offset:41088
	s_waitcnt vmcnt(6) lgkmcnt(1)
	v_mfma_f32_32x32x16_bf16 v[18:33], v[52:55], v[122:125], v[18:33]
	s_waitcnt lgkmcnt(0)
	v_mfma_f32_32x32x16_bf16 v[2:17], v[56:59], v[122:125], v[2:17]
	ds_read_b128 v[52:55], v189 offset:32896
	ds_read_b128 v[56:59], v189 offset:41088
	s_waitcnt vmcnt(5) lgkmcnt(1)
	v_mfma_f32_32x32x16_bf16 v[18:33], v[52:55], v[118:121], v[18:33]
	s_waitcnt lgkmcnt(0)
	v_mfma_f32_32x32x16_bf16 v[2:17], v[56:59], v[118:121], v[2:17]
	ds_read_b128 v[52:55], v188 offset:32896
	ds_read_b128 v[56:59], v188 offset:41088
	s_waitcnt vmcnt(4) lgkmcnt(1)
	v_mfma_f32_32x32x16_bf16 v[18:33], v[52:55], v[114:117], v[18:33]
	v_add_u32_e32 v52, 0, v162
	v_add_u32_e32 v80, 0x10880, v52
	s_waitcnt lgkmcnt(0)
	v_mfma_f32_32x32x16_bf16 v[2:17], v[56:59], v[114:117], v[2:17]
	ds_read_b128 v[52:55], v51
	ds_read_b128 v[56:59], v51 offset:32
	ds_read_b128 v[60:63], v80
	ds_read_b128 v[64:67], v80 offset:32
	ds_read_b128 v[68:71], v51 offset:64
	ds_read_b128 v[72:75], v80 offset:64
	ds_read_b128 v[76:79], v51 offset:96
	ds_read_b128 v[80:83], v80 offset:96
	s_waitcnt lgkmcnt(7)
	s_waitcnt lgkmcnt(6)
	s_waitcnt lgkmcnt(3)
	v_xor_b32_e32 v71, 0x80000000, v71
	v_xor_b32_e32 v70, 0x80000000, v70
	s_waitcnt lgkmcnt(1)
	v_xor_b32_e32 v79, 0x80000000, v79
	v_xor_b32_e32 v78, 0x80000000, v78
	v_fma_f32 v24, v24, s12, -v58
	v_fma_f32 v25, v25, s12, -v59
	v_fma_f32 v22, v22, s12, -v56
	v_fma_f32 v23, v23, s12, -v57
	v_fma_f32 v20, v20, s12, -v54
	v_fma_f32 v21, v21, s12, -v55
	v_fma_f32 v18, v18, s12, -v52
	v_fma_f32 v19, v19, s12, -v53
	v_xor_b32_e32 v53, 0x80000000, v63
	v_xor_b32_e32 v52, 0x80000000, v62
	v_xor_b32_e32 v55, 0x80000000, v67
	v_xor_b32_e32 v54, 0x80000000, v66
	v_xor_b32_e32 v57, 0x80000000, v75
	v_xor_b32_e32 v56, 0x80000000, v74
	s_waitcnt lgkmcnt(0)
	v_xor_b32_e32 v59, 0x80000000, v83
	v_xor_b32_e32 v58, 0x80000000, v82
	v_fma_f32 v32, v32, s12, v78
	v_fma_f32 v33, v33, s12, v79
	v_fma_f32 v30, v30, s12, -v76
	v_fma_f32 v31, v31, s12, -v77
	v_fma_f32 v28, v28, s12, v70
	v_fma_f32 v29, v29, s12, v71
	v_fma_f32 v26, v26, s12, -v68
	v_fma_f32 v27, v27, s12, -v69
	v_fma_f32 v16, v16, s12, v58
	v_fma_f32 v17, v17, s12, v59
	v_fma_f32 v14, v14, s12, -v80
	v_fma_f32 v15, v15, s12, -v81
	v_fma_f32 v12, v12, s12, v56
	v_fma_f32 v13, v13, s12, v57
	v_fma_f32 v10, v10, s12, -v72
	v_fma_f32 v11, v11, s12, -v73
	v_fma_f32 v8, v8, s12, v54
	v_fma_f32 v9, v9, s12, v55
	v_fma_f32 v6, v6, s12, -v64
	v_fma_f32 v7, v7, s12, -v65
	v_fma_f32 v4, v4, s12, v52
	v_fma_f32 v5, v5, s12, v53
	v_fma_f32 v2, v2, s12, -v60
	v_fma_f32 v3, v3, s12, -v61
	s_cbranch_scc1 .LBB0_643
	v_cmp_gt_i32_e64 s[92:93], 26, v187
	v_cmp_gt_i32_e64 s[94:95], 27, v187
	v_cmp_gt_i32_e64 s[90:91], 25, v187
	s_and_b64 s[92:93], s[94:95], s[92:93]
	v_cmp_gt_i32_e64 s[88:89], 24, v187
	s_and_b64 s[90:91], s[92:93], s[90:91]
	v_cmp_gt_i32_e64 s[86:87], 19, v187
	s_and_b64 s[88:89], s[90:91], s[88:89]
	v_cmp_gt_i32_e64 s[84:85], 18, v187
	s_and_b64 s[86:87], s[88:89], s[86:87]
	v_cmp_gt_i32_e64 s[82:83], 17, v187
	s_and_b64 s[84:85], s[86:87], s[84:85]
	v_cmp_gt_i32_e64 s[80:81], 16, v187
	s_and_b64 s[82:83], s[84:85], s[82:83]
	v_cmp_gt_i32_e64 s[78:79], 11, v187
	s_and_b64 s[80:81], s[82:83], s[80:81]
	v_cmp_gt_i32_e64 s[76:77], 10, v187
	s_and_b64 s[78:79], s[80:81], s[78:79]
	v_cmp_gt_i32_e64 s[74:75], 9, v187
	s_and_b64 s[76:77], s[78:79], s[76:77]
	v_cmp_gt_i32_e64 s[72:73], 8, v187
	s_and_b64 s[74:75], s[76:77], s[74:75]
	v_cmp_gt_i32_e64 s[70:71], 3, v187
	s_and_b64 s[72:73], s[74:75], s[72:73]
	v_cmp_gt_i32_e64 s[68:69], 2, v187
	s_and_b64 s[70:71], s[72:73], s[70:71]
	v_cmp_gt_i32_e64 s[2:3], 1, v187
	s_and_b64 s[68:69], s[70:71], s[68:69]
	v_cmp_gt_i32_e64 s[0:1], 0, v187
	s_and_b64 s[2:3], s[68:69], s[2:3]
	s_and_b64 s[0:1], s[2:3], s[0:1]
	v_cmp_gt_i32_e64 s[66:67], 58, v187
	v_cndmask_b32_e64 v18, v18, v175, s[0:1]
	v_cmp_gt_i32_e64 s[0:1], 59, v187
	v_cmp_gt_i32_e64 s[64:65], 57, v187
	v_cmp_gt_i32_e64 s[62:63], 56, v187
	v_cndmask_b32_e64 v17, v17, v175, s[0:1]
	s_and_b64 s[0:1], s[0:1], s[66:67]
	v_cndmask_b32_e64 v16, v16, v175, s[0:1]
	s_and_b64 s[0:1], s[0:1], s[64:65]
	v_cmp_gt_i32_e64 s[60:61], 51, v187
	v_cndmask_b32_e64 v15, v15, v175, s[0:1]
	s_and_b64 s[0:1], s[0:1], s[62:63]
	v_cmp_gt_i32_e64 s[58:59], 50, v187
	v_cndmask_b32_e64 v14, v14, v175, s[0:1]
	s_and_b64 s[0:1], s[0:1], s[60:61]
	v_cmp_gt_i32_e64 s[56:57], 49, v187
	v_cndmask_b32_e64 v13, v13, v175, s[0:1]
	s_and_b64 s[0:1], s[0:1], s[58:59]
	v_cmp_gt_i32_e64 s[54:55], 48, v187
	v_cndmask_b32_e64 v12, v12, v175, s[0:1]
	s_and_b64 s[0:1], s[0:1], s[56:57]
	v_cmp_gt_i32_e64 s[52:53], 43, v187
	v_cndmask_b32_e64 v11, v11, v175, s[0:1]
	s_and_b64 s[0:1], s[0:1], s[54:55]
	v_cmp_gt_i32_e64 s[50:51], 42, v187
	v_cndmask_b32_e64 v10, v10, v175, s[0:1]
	s_and_b64 s[0:1], s[0:1], s[52:53]
	v_cmp_gt_i32_e64 s[48:49], 41, v187
	v_cndmask_b32_e64 v9, v9, v175, s[0:1]
	s_and_b64 s[0:1], s[0:1], s[50:51]
	v_cmp_gt_i32_e64 s[46:47], 40, v187
	v_cndmask_b32_e64 v8, v8, v175, s[0:1]
	s_and_b64 s[0:1], s[0:1], s[48:49]
	v_cmp_gt_i32_e64 s[44:45], 35, v187
	v_cndmask_b32_e64 v7, v7, v175, s[0:1]
	s_and_b64 s[0:1], s[0:1], s[46:47]
	v_cmp_gt_i32_e64 s[42:43], 34, v187
	v_cndmask_b32_e64 v6, v6, v175, s[0:1]
	s_and_b64 s[0:1], s[0:1], s[44:45]
	v_cmp_gt_i32_e64 s[40:41], 33, v187
	v_cndmask_b32_e64 v5, v5, v175, s[0:1]
	s_and_b64 s[0:1], s[0:1], s[42:43]
	v_cmp_gt_i32_e32 vcc, 32, v187
	v_cndmask_b32_e64 v4, v4, v175, s[0:1]
	s_and_b64 s[0:1], s[0:1], s[40:41]
	v_cndmask_b32_e64 v30, v30, v175, s[88:89]
	v_readlane_b32 s88, v242, 2
	s_and_b64 vcc, s[0:1], vcc
	v_cndmask_b32_e64 v33, v33, v175, s[94:95]
	v_cndmask_b32_e64 v32, v32, v175, s[92:93]
	s_movk_i32 s93, 0x6018
	s_mov_b32 s92, 0xf800000
	v_cndmask_b32_e64 v31, v31, v175, s[90:91]
	s_mov_b64 s[90:91], s[16:17]
	v_readlane_b32 s89, v242, 3
	v_cndmask_b32_e64 v29, v29, v175, s[86:87]
	v_readlane_b32 s86, v242, 0
	v_cndmask_b32_e64 v28, v28, v175, s[84:85]
	v_cndmask_b32_e64 v27, v27, v175, s[82:83]
	s_movk_i32 s83, 0x6000
	v_cndmask_b32_e64 v26, v26, v175, s[80:81]
	v_cndmask_b32_e64 v25, v25, v175, s[78:79]
	v_cndmask_b32_e64 v24, v24, v175, s[76:77]
	v_cndmask_b32_e64 v23, v23, v175, s[74:75]
	v_cndmask_b32_e64 v22, v22, v175, s[72:73]
	v_cndmask_b32_e64 v21, v21, v175, s[70:71]
	v_cndmask_b32_e64 v20, v20, v175, s[68:69]
	v_cndmask_b32_e64 v19, v19, v175, s[2:3]
	s_mov_b32 s56, s30
	v_cndmask_b32_e64 v3, v3, v175, s[0:1]
	v_cndmask_b32_e32 v2, v2, v175, vcc
	v_readlane_b32 s87, v242, 1

.Lmskip_fox_1:
	ds_read_b128 v[66:69], v198
	ds_read_b128 v[70:73], v198 offset:32
	ds_read_b128 v[202:205], v198 offset:128
	ds_read_b128 v[206:209], v198 offset:160
	ds_read_b128 v[76:79], v198 offset:64
	ds_read_b128 v[210:213], v198 offset:96
	ds_read_b128 v[214:217], v198 offset:192
	ds_read_b128 v[220:223], v198 offset:224
	s_waitcnt lgkmcnt(7)
	s_waitcnt lgkmcnt(3)
	v_xor_b32_e32 v225, 0x80000000, v79
	v_xor_b32_e32 v224, 0x80000000, v78
	s_waitcnt lgkmcnt(2)
	v_fma_f32 v74, v110, s12, -v210
	v_fma_f32 v75, v111, s12, -v211
	v_fma_f32 v78, v106, s12, -v76
	v_fma_f32 v79, v107, s12, -v77
	v_fma_f32 v102, v102, s12, -v70
	v_fma_f32 v103, v103, s12, -v71
	v_fma_f32 v106, v108, s12, v224
	v_fma_f32 v107, v109, s12, v225
	v_xor_b32_e32 v109, 0x80000000, v205
	v_xor_b32_e32 v108, 0x80000000, v204
	v_xor_b32_e32 v111, 0x80000000, v209
	v_xor_b32_e32 v110, 0x80000000, v208
	s_waitcnt lgkmcnt(1)
	s_waitcnt lgkmcnt(0)
	v_fma_f32 v80, v112, s12, -v212
	v_fma_f32 v81, v113, s12, -v213
	v_fma_f32 v104, v104, s12, -v72
	v_fma_f32 v105, v105, s12, -v73
	v_fma_f32 v100, v100, s12, -v68
	v_fma_f32 v101, v101, s12, -v69
	v_fma_f32 v98, v98, s12, -v66
	v_fma_f32 v99, v99, s12, -v67
	v_fma_f32 v66, v94, s12, -v220
	v_fma_f32 v67, v95, s12, -v221
	v_fma_f32 v68, v90, s12, -v214
	v_fma_f32 v69, v91, s12, -v215
	v_fma_f32 v72, v86, s12, -v206
	v_fma_f32 v73, v87, s12, -v207
	v_fma_f32 v70, v96, s12, -v222
	v_fma_f32 v71, v97, s12, -v223
	v_fma_f32 v76, v92, s12, -v216
	v_fma_f32 v77, v93, s12, -v217
	v_fma_f32 v86, v88, s12, v110
	v_fma_f32 v87, v89, s12, v111
	v_fma_f32 v84, v84, s12, v108
	v_fma_f32 v85, v85, s12, v109
	s_cmp_le_i32 s11, s27
	v_fma_f32 v82, v82, s12, -v202
	v_fma_f32 v83, v83, s12, -v203
	s_cbranch_scc1 .LBB0_647
	v_add_u32_e32 v1, 64, v199
	v_cmp_gt_i32_e64 s[92:93], 26, v1
	v_cmp_gt_i32_e64 s[94:95], 27, v1
	v_cmp_gt_i32_e64 s[90:91], 25, v1
	s_and_b64 s[92:93], s[94:95], s[92:93]
	v_cmp_gt_i32_e64 s[88:89], 24, v1
	s_and_b64 s[90:91], s[92:93], s[90:91]
	v_cmp_gt_i32_e64 s[86:87], 19, v1
	s_and_b64 s[88:89], s[90:91], s[88:89]
	v_cmp_gt_i32_e64 s[84:85], 18, v1
	s_and_b64 s[86:87], s[88:89], s[86:87]
	v_cmp_gt_i32_e64 s[82:83], 17, v1
	s_and_b64 s[84:85], s[86:87], s[84:85]
	v_cmp_gt_i32_e64 s[80:81], 16, v1
	s_and_b64 s[82:83], s[84:85], s[82:83]
	v_cmp_gt_i32_e64 s[78:79], 11, v1
	s_and_b64 s[80:81], s[82:83], s[80:81]
	v_cmp_gt_i32_e64 s[76:77], 10, v1
	s_and_b64 s[78:79], s[80:81], s[78:79]
	v_cmp_gt_i32_e64 s[74:75], 9, v1
	s_and_b64 s[76:77], s[78:79], s[76:77]
	v_cmp_gt_i32_e64 s[72:73], 8, v1
	s_and_b64 s[74:75], s[76:77], s[74:75]
	v_cmp_gt_i32_e64 s[70:71], 3, v1
	s_and_b64 s[72:73], s[74:75], s[72:73]
	v_cmp_gt_i32_e64 s[68:69], 2, v1
	s_and_b64 s[70:71], s[72:73], s[70:71]
	v_cmp_gt_i32_e64 s[2:3], 1, v1
	s_and_b64 s[68:69], s[70:71], s[68:69]
	v_cmp_gt_i32_e64 s[0:1], 0, v1
	s_and_b64 s[2:3], s[68:69], s[2:3]
	s_and_b64 s[0:1], s[2:3], s[0:1]
	v_cmp_gt_i32_e64 s[66:67], 58, v1
	v_cndmask_b32_e64 v98, v98, v175, s[0:1]
	v_cmp_gt_i32_e64 s[0:1], 59, v1
	v_cmp_gt_i32_e64 s[64:65], 57, v1
	v_cmp_gt_i32_e64 s[62:63], 56, v1
	v_cndmask_b32_e64 v71, v71, v175, s[0:1]
	s_and_b64 s[0:1], s[0:1], s[66:67]
	v_cndmask_b32_e64 v70, v70, v175, s[0:1]
	s_and_b64 s[0:1], s[0:1], s[64:65]
	v_cmp_gt_i32_e64 s[60:61], 51, v1
	v_cndmask_b32_e64 v67, v67, v175, s[0:1]
	s_and_b64 s[0:1], s[0:1], s[62:63]
	v_cmp_gt_i32_e64 s[58:59], 50, v1
	v_cndmask_b32_e64 v66, v66, v175, s[0:1]
	s_and_b64 s[0:1], s[0:1], s[60:61]
	v_cmp_gt_i32_e64 s[56:57], 49, v1
	v_cndmask_b32_e64 v77, v77, v175, s[0:1]
	s_and_b64 s[0:1], s[0:1], s[58:59]
	v_cmp_gt_i32_e64 s[54:55], 48, v1
	v_cndmask_b32_e64 v76, v76, v175, s[0:1]
	s_and_b64 s[0:1], s[0:1], s[56:57]
	v_cmp_gt_i32_e64 s[52:53], 43, v1
	v_cndmask_b32_e64 v69, v69, v175, s[0:1]
	s_and_b64 s[0:1], s[0:1], s[54:55]
	v_cmp_gt_i32_e64 s[50:51], 42, v1
	v_cndmask_b32_e64 v68, v68, v175, s[0:1]
	s_and_b64 s[0:1], s[0:1], s[52:53]
	v_cmp_gt_i32_e64 s[48:49], 41, v1
	v_cndmask_b32_e64 v87, v87, v175, s[0:1]
	s_and_b64 s[0:1], s[0:1], s[50:51]
	v_cmp_gt_i32_e64 s[46:47], 40, v1
	v_cndmask_b32_e64 v86, v86, v175, s[0:1]
	s_and_b64 s[0:1], s[0:1], s[48:49]
	v_cmp_gt_i32_e64 s[44:45], 35, v1
	v_cndmask_b32_e64 v73, v73, v175, s[0:1]
	s_and_b64 s[0:1], s[0:1], s[46:47]
	v_cmp_gt_i32_e64 s[42:43], 34, v1
	v_cndmask_b32_e64 v72, v72, v175, s[0:1]
	s_and_b64 s[0:1], s[0:1], s[44:45]
	v_cmp_gt_i32_e64 s[40:41], 33, v1
	v_cndmask_b32_e64 v85, v85, v175, s[0:1]
	s_and_b64 s[0:1], s[0:1], s[42:43]
	v_cmp_gt_i32_e32 vcc, 32, v1
	v_cndmask_b32_e64 v84, v84, v175, s[0:1]
	s_and_b64 s[0:1], s[0:1], s[40:41]
	v_cndmask_b32_e64 v74, v74, v175, s[88:89]
	v_readlane_b32 s88, v242, 2
	s_and_b64 vcc, s[0:1], vcc
	v_cndmask_b32_e64 v81, v81, v175, s[94:95]
	v_cndmask_b32_e64 v80, v80, v175, s[92:93]
	s_movk_i32 s93, 0x6018
	s_mov_b32 s92, 0xf800000
	v_cndmask_b32_e64 v75, v75, v175, s[90:91]
	s_mov_b64 s[90:91], s[16:17]
	v_readlane_b32 s89, v242, 3
	v_cndmask_b32_e64 v107, v107, v175, s[86:87]
	v_readlane_b32 s86, v242, 0
	v_cndmask_b32_e64 v106, v106, v175, s[84:85]
	v_cndmask_b32_e64 v79, v79, v175, s[82:83]
	s_movk_i32 s83, 0x6000
	v_cndmask_b32_e64 v78, v78, v175, s[80:81]
	v_cndmask_b32_e64 v105, v105, v175, s[78:79]
	v_cndmask_b32_e64 v104, v104, v175, s[76:77]
	v_cndmask_b32_e64 v103, v103, v175, s[74:75]
	v_cndmask_b32_e64 v102, v102, v175, s[72:73]
	v_cndmask_b32_e64 v101, v101, v175, s[70:71]
	v_cndmask_b32_e64 v100, v100, v175, s[68:69]
	v_cndmask_b32_e64 v99, v99, v175, s[2:3]
	s_mov_b32 s56, s30
	v_cndmask_b32_e64 v83, v83, v175, s[0:1]
	v_cndmask_b32_e32 v82, v82, v175, vcc
	v_readlane_b32 s87, v242, 1

.Lmskip_fox_3:
	ds_read_b128 v[100:103], v198 offset:256
	ds_read_b128 v[110:113], v198 offset:288
	ds_read_b128 v[202:205], v198 offset:384
	ds_read_b128 v[206:209], v198 offset:416
	ds_read_b128 v[210:213], v198 offset:320
	ds_read_b128 v[214:217], v198 offset:352
	ds_read_b128 v[218:221], v198 offset:448
	ds_read_b128 v[222:225], v198 offset:480
	s_waitcnt lgkmcnt(7)
	s_waitcnt lgkmcnt(6)
	v_xor_b32_e32 v107, 0x80000000, v113
	v_xor_b32_e32 v106, 0x80000000, v112
	s_waitcnt lgkmcnt(3)
	v_xor_b32_e32 v113, 0x80000000, v213
	v_xor_b32_e32 v112, 0x80000000, v212
	s_waitcnt lgkmcnt(2)
	v_xor_b32_e32 v213, 0x80000000, v217
	v_xor_b32_e32 v212, 0x80000000, v216
	v_fma_f32 v98, v86, s12, -v110
	v_fma_f32 v99, v87, s12, -v111
	v_fma_f32 v86, v96, s12, v212
	v_fma_f32 v87, v97, s12, v213
	v_fma_f32 v88, v88, s12, v106
	v_fma_f32 v89, v89, s12, v107
	v_fma_f32 v84, v84, s12, -v102
	v_fma_f32 v85, v85, s12, -v103
	v_fma_f32 v96, v82, s12, -v100
	v_fma_f32 v97, v83, s12, -v101
	s_waitcnt lgkmcnt(1)
	v_xor_b32_e32 v107, 0x80000000, v221
	v_xor_b32_e32 v106, 0x80000000, v220
	s_waitcnt lgkmcnt(0)
	v_xor_b32_e32 v111, 0x80000000, v225
	v_xor_b32_e32 v110, 0x80000000, v224
	s_add_i32 s0, s11, 64
	v_fma_f32 v94, v94, s12, -v214
	v_fma_f32 v95, v95, s12, -v215
	v_fma_f32 v90, v90, s12, -v210
	v_fma_f32 v91, v91, s12, -v211
	v_fma_f32 v92, v92, s12, v112
	v_fma_f32 v93, v93, s12, v113
	v_fma_f32 v82, v78, s12, -v222
	v_fma_f32 v83, v79, s12, -v223
	v_fma_f32 v74, v74, s12, -v218
	v_fma_f32 v75, v75, s12, -v219
	v_fma_f32 v78, v70, s12, -v206
	v_fma_f32 v79, v71, s12, -v207
	v_fma_f32 v70, v80, s12, v110
	v_fma_f32 v71, v81, s12, v111
	v_fma_f32 v76, v76, s12, v106
	v_fma_f32 v77, v77, s12, v107
	v_fma_f32 v100, v72, s12, -v208
	v_fma_f32 v101, v73, s12, -v209
	v_fma_f32 v102, v68, s12, -v204
	v_fma_f32 v103, v69, s12, -v205
	s_cmp_le_i32 s0, s27
	v_fma_f32 v80, v66, s12, -v202
	v_fma_f32 v81, v67, s12, -v203
	s_cbranch_scc1 .LBB0_655
	v_cmp_gt_i32_e64 s[92:93], 26, v199
	v_cmp_gt_i32_e64 s[94:95], 27, v199
	v_cmp_gt_i32_e64 s[90:91], 25, v199
	s_and_b64 s[92:93], s[94:95], s[92:93]
	v_cmp_gt_i32_e64 s[88:89], 24, v199
	s_and_b64 s[90:91], s[92:93], s[90:91]
	v_cmp_gt_i32_e64 s[86:87], 19, v199
	s_and_b64 s[88:89], s[90:91], s[88:89]
	v_cmp_gt_i32_e64 s[84:85], 18, v199
	s_and_b64 s[86:87], s[88:89], s[86:87]
	v_cmp_gt_i32_e64 s[82:83], 17, v199
	s_and_b64 s[84:85], s[86:87], s[84:85]
	v_cmp_gt_i32_e64 s[80:81], 16, v199
	s_and_b64 s[82:83], s[84:85], s[82:83]
	v_cmp_gt_i32_e64 s[78:79], 11, v199
	s_and_b64 s[80:81], s[82:83], s[80:81]
	v_cmp_gt_i32_e64 s[76:77], 10, v199
	s_and_b64 s[78:79], s[80:81], s[78:79]
	v_cmp_gt_i32_e64 s[74:75], 9, v199
	s_and_b64 s[76:77], s[78:79], s[76:77]
	v_cmp_gt_i32_e64 s[72:73], 8, v199
	s_and_b64 s[74:75], s[76:77], s[74:75]
	v_cmp_gt_i32_e64 s[70:71], 3, v199
	s_and_b64 s[72:73], s[74:75], s[72:73]
	v_cmp_gt_i32_e64 s[68:69], 2, v199
	s_and_b64 s[70:71], s[72:73], s[70:71]
	v_cmp_gt_i32_e64 s[2:3], 1, v199
	s_and_b64 s[68:69], s[70:71], s[68:69]
	v_cmp_gt_i32_e64 s[0:1], 0, v199
	s_and_b64 s[2:3], s[68:69], s[2:3]
	s_and_b64 s[0:1], s[2:3], s[0:1]
	v_cmp_gt_i32_e64 s[66:67], 58, v199
	v_cndmask_b32_e64 v96, v96, v175, s[0:1]
	v_cmp_gt_i32_e64 s[0:1], 59, v199
	v_cmp_gt_i32_e64 s[64:65], 57, v199
	v_cmp_gt_i32_e64 s[62:63], 56, v199
	v_cndmask_b32_e64 v71, v71, v175, s[0:1]
	s_and_b64 s[0:1], s[0:1], s[66:67]
	v_cndmask_b32_e64 v70, v70, v175, s[0:1]
	s_and_b64 s[0:1], s[0:1], s[64:65]
	v_cmp_gt_i32_e64 s[60:61], 51, v199
	v_cndmask_b32_e64 v83, v83, v175, s[0:1]
	s_and_b64 s[0:1], s[0:1], s[62:63]
	v_cmp_gt_i32_e64 s[58:59], 50, v199
	v_cndmask_b32_e64 v82, v82, v175, s[0:1]
	s_and_b64 s[0:1], s[0:1], s[60:61]
	v_cmp_gt_i32_e64 s[56:57], 49, v199
	v_cndmask_b32_e64 v77, v77, v175, s[0:1]
	s_and_b64 s[0:1], s[0:1], s[58:59]
	v_cmp_gt_i32_e64 s[54:55], 48, v199
	v_cndmask_b32_e64 v76, v76, v175, s[0:1]
	s_and_b64 s[0:1], s[0:1], s[56:57]
	v_cmp_gt_i32_e64 s[52:53], 43, v199
	v_cndmask_b32_e64 v75, v75, v175, s[0:1]
	s_and_b64 s[0:1], s[0:1], s[54:55]
	v_cmp_gt_i32_e64 s[50:51], 42, v199
	v_cndmask_b32_e64 v74, v74, v175, s[0:1]
	s_and_b64 s[0:1], s[0:1], s[52:53]
	v_cmp_gt_i32_e64 s[48:49], 41, v199
	v_cndmask_b32_e64 v101, v101, v175, s[0:1]
	s_and_b64 s[0:1], s[0:1], s[50:51]
	v_cmp_gt_i32_e64 s[46:47], 40, v199
	v_cndmask_b32_e64 v100, v100, v175, s[0:1]
	s_and_b64 s[0:1], s[0:1], s[48:49]
	v_cmp_gt_i32_e64 s[44:45], 35, v199
	v_cndmask_b32_e64 v79, v79, v175, s[0:1]
	s_and_b64 s[0:1], s[0:1], s[46:47]
	v_cmp_gt_i32_e64 s[42:43], 34, v199
	v_cndmask_b32_e64 v78, v78, v175, s[0:1]
	s_and_b64 s[0:1], s[0:1], s[44:45]
	v_cmp_gt_i32_e64 s[40:41], 33, v199
	v_cndmask_b32_e64 v103, v103, v175, s[0:1]
	s_and_b64 s[0:1], s[0:1], s[42:43]
	v_cmp_gt_i32_e32 vcc, 32, v199
	v_cndmask_b32_e64 v102, v102, v175, s[0:1]
	s_and_b64 s[0:1], s[0:1], s[40:41]
	v_cndmask_b32_e64 v94, v94, v175, s[88:89]
	v_readlane_b32 s88, v242, 2
	s_and_b64 vcc, s[0:1], vcc
	v_cndmask_b32_e64 v87, v87, v175, s[94:95]
	v_cndmask_b32_e64 v86, v86, v175, s[92:93]
	s_movk_i32 s93, 0x6018
	s_mov_b32 s92, 0xf800000
	v_cndmask_b32_e64 v95, v95, v175, s[90:91]
	s_mov_b64 s[90:91], s[16:17]
	v_readlane_b32 s89, v242, 3
	v_cndmask_b32_e64 v93, v93, v175, s[86:87]
	v_readlane_b32 s86, v242, 0
	v_cndmask_b32_e64 v92, v92, v175, s[84:85]
	v_cndmask_b32_e64 v91, v91, v175, s[82:83]
	s_movk_i32 s83, 0x6000
	v_cndmask_b32_e64 v90, v90, v175, s[80:81]
	v_cndmask_b32_e64 v89, v89, v175, s[78:79]
	v_cndmask_b32_e64 v88, v88, v175, s[76:77]
	v_cndmask_b32_e64 v99, v99, v175, s[74:75]
	v_cndmask_b32_e64 v98, v98, v175, s[72:73]
	v_cndmask_b32_e64 v85, v85, v175, s[70:71]
	v_cndmask_b32_e64 v84, v84, v175, s[68:69]
	v_cndmask_b32_e64 v97, v97, v175, s[2:3]
	s_mov_b32 s56, s30
	v_cndmask_b32_e64 v81, v81, v175, s[0:1]
	v_cndmask_b32_e32 v80, v80, v175, vcc
	v_readlane_b32 s87, v242, 1

.Lmskip_fox_5:
	s_lshl_b32 s1, s25, 6
	s_sub_i32 s0, s1, 64
	s_lshl_b32 s2, s0, 2
	s_add_i32 s2, s2, 0
	v_lshl_add_u32 v66, v186, 2, s2
	v_add_u32_e32 v66, 0x10800, v66
	s_add_i32 s1, s1, -1
	s_cmp_gt_i32 s1, s27
	ds_read_b128 v[116:119], v66 offset:128
	ds_read_b128 v[120:123], v66
	ds_read_b128 v[68:71], v66 offset:32
	ds_read_b128 v[124:127], v66 offset:160
	ds_read_b128 v[72:75], v66 offset:64
	ds_read_b128 v[128:131], v66 offset:192
	ds_read_b128 v[76:79], v66 offset:96
	ds_read_b128 v[132:135], v66 offset:224
	s_waitcnt lgkmcnt(6)
	v_xor_b32_e32 v81, 0x80000000, v123
	v_xor_b32_e32 v80, 0x80000000, v122
	s_waitcnt lgkmcnt(5)
	v_xor_b32_e32 v123, 0x80000000, v71
	v_xor_b32_e32 v122, 0x80000000, v70
	s_waitcnt lgkmcnt(1)
	v_xor_b32_e32 v137, 0x80000000, v75
	v_xor_b32_e32 v136, 0x80000000, v74
	v_fma_f32 v66, v110, s12, -v76
	v_fma_f32 v67, v111, s12, -v77
	v_fma_f32 v70, v106, s12, -v72
	v_fma_f32 v71, v107, s12, -v73
	v_fma_f32 v74, v102, s12, -v68
	v_fma_f32 v75, v103, s12, -v69
	v_fma_f32 v68, v112, s12, -v78
	v_fma_f32 v69, v113, s12, -v79
	v_fma_f32 v76, v104, s12, v122
	v_fma_f32 v77, v105, s12, v123
	v_fma_f32 v78, v100, s12, v80
	v_fma_f32 v79, v101, s12, v81
	v_xor_b32_e32 v101, 0x80000000, v119
	v_xor_b32_e32 v100, 0x80000000, v118
	v_xor_b32_e32 v103, 0x80000000, v127
	v_xor_b32_e32 v102, 0x80000000, v126
	v_xor_b32_e32 v105, 0x80000000, v131
	v_xor_b32_e32 v104, 0x80000000, v130
	s_waitcnt lgkmcnt(0)
	v_xor_b32_e32 v107, 0x80000000, v135
	v_xor_b32_e32 v106, 0x80000000, v134
	v_fma_f32 v72, v108, s12, v136
	v_fma_f32 v73, v109, s12, v137
	v_fma_f32 v80, v98, s12, -v120
	v_fma_f32 v81, v99, s12, -v121
	v_fma_f32 v94, v94, s12, -v132
	v_fma_f32 v95, v95, s12, -v133
	v_fma_f32 v90, v90, s12, -v128
	v_fma_f32 v91, v91, s12, -v129
	v_fma_f32 v98, v86, s12, -v124
	v_fma_f32 v99, v87, s12, -v125
	v_fma_f32 v86, v96, s12, v106
	v_fma_f32 v87, v97, s12, v107
	v_fma_f32 v92, v92, s12, v104
	v_fma_f32 v93, v93, s12, v105
	v_fma_f32 v88, v88, s12, v102
	v_fma_f32 v89, v89, s12, v103
	v_fma_f32 v84, v84, s12, v100
	v_fma_f32 v85, v85, s12, v101
	v_fma_f32 v82, v82, s12, -v116
	v_fma_f32 v83, v83, s12, -v117
	s_cbranch_scc0 .LBB0_666
	v_subrev_u32_e32 v96, s0, v187
	v_cmp_gt_i32_e64 s[92:93], 26, v96
	v_cmp_gt_i32_e64 s[94:95], 27, v96
	v_cmp_gt_i32_e64 s[90:91], 25, v96
	s_and_b64 s[92:93], s[94:95], s[92:93]
	v_cmp_gt_i32_e64 s[88:89], 24, v96
	s_and_b64 s[90:91], s[92:93], s[90:91]
	v_cmp_gt_i32_e64 s[86:87], 19, v96
	s_and_b64 s[88:89], s[90:91], s[88:89]
	v_cmp_gt_i32_e64 s[84:85], 18, v96
	s_and_b64 s[86:87], s[88:89], s[86:87]
	v_cmp_gt_i32_e64 s[82:83], 17, v96
	s_and_b64 s[84:85], s[86:87], s[84:85]
	v_cmp_gt_i32_e64 s[80:81], 16, v96
	s_and_b64 s[82:83], s[84:85], s[82:83]
	v_cmp_gt_i32_e64 s[78:79], 11, v96
	s_and_b64 s[80:81], s[82:83], s[80:81]
	v_cmp_gt_i32_e64 s[76:77], 10, v96
	s_and_b64 s[78:79], s[80:81], s[78:79]
	v_cmp_gt_i32_e64 s[74:75], 9, v96
	s_and_b64 s[76:77], s[78:79], s[76:77]
	v_cmp_gt_i32_e64 s[72:73], 8, v96
	s_and_b64 s[74:75], s[76:77], s[74:75]
	v_cmp_gt_i32_e64 s[70:71], 3, v96
	s_and_b64 s[72:73], s[74:75], s[72:73]
	v_cmp_gt_i32_e64 s[68:69], 2, v96
	s_and_b64 s[70:71], s[72:73], s[70:71]
	v_cmp_gt_i32_e64 s[2:3], 1, v96
	s_and_b64 s[68:69], s[70:71], s[68:69]
	v_cmp_gt_i32_e64 s[0:1], 0, v96
	s_and_b64 s[2:3], s[68:69], s[2:3]
	s_and_b64 s[0:1], s[2:3], s[0:1]
	v_cmp_gt_i32_e64 s[66:67], 58, v96
	v_cndmask_b32_e64 v80, v80, v175, s[0:1]
	v_cmp_gt_i32_e64 s[0:1], 59, v96
	v_cmp_gt_i32_e64 s[64:65], 57, v96
	v_cmp_gt_i32_e64 s[62:63], 56, v96
	v_cndmask_b32_e64 v87, v87, v175, s[0:1]
	s_and_b64 s[0:1], s[0:1], s[66:67]
	v_cndmask_b32_e64 v86, v86, v175, s[0:1]
	s_and_b64 s[0:1], s[0:1], s[64:65]
	v_cmp_gt_i32_e64 s[60:61], 51, v96
	v_cndmask_b32_e64 v95, v95, v175, s[0:1]
	s_and_b64 s[0:1], s[0:1], s[62:63]
	v_cmp_gt_i32_e64 s[58:59], 50, v96
	v_cndmask_b32_e64 v94, v94, v175, s[0:1]
	s_and_b64 s[0:1], s[0:1], s[60:61]
	v_cmp_gt_i32_e64 s[56:57], 49, v96
	v_cndmask_b32_e64 v93, v93, v175, s[0:1]
	s_and_b64 s[0:1], s[0:1], s[58:59]
	v_cmp_gt_i32_e64 s[54:55], 48, v96
	v_cndmask_b32_e64 v92, v92, v175, s[0:1]
	s_and_b64 s[0:1], s[0:1], s[56:57]
	v_cmp_gt_i32_e64 s[52:53], 43, v96
	v_cndmask_b32_e64 v91, v91, v175, s[0:1]
	s_and_b64 s[0:1], s[0:1], s[54:55]
	v_cmp_gt_i32_e64 s[50:51], 42, v96
	v_cndmask_b32_e64 v90, v90, v175, s[0:1]
	s_and_b64 s[0:1], s[0:1], s[52:53]
	v_cmp_gt_i32_e64 s[48:49], 41, v96
	v_cndmask_b32_e64 v89, v89, v175, s[0:1]
	s_and_b64 s[0:1], s[0:1], s[50:51]
	v_cmp_gt_i32_e64 s[46:47], 40, v96
	v_cndmask_b32_e64 v88, v88, v175, s[0:1]
	s_and_b64 s[0:1], s[0:1], s[48:49]
	v_cmp_gt_i32_e64 s[44:45], 35, v96
	v_cndmask_b32_e64 v99, v99, v175, s[0:1]
	s_and_b64 s[0:1], s[0:1], s[46:47]
	v_cmp_gt_i32_e64 s[42:43], 34, v96
	v_cndmask_b32_e64 v98, v98, v175, s[0:1]
	s_and_b64 s[0:1], s[0:1], s[44:45]
	v_cmp_gt_i32_e64 s[40:41], 33, v96
	v_cndmask_b32_e64 v85, v85, v175, s[0:1]
	s_and_b64 s[0:1], s[0:1], s[42:43]
	v_cmp_gt_i32_e32 vcc, 32, v96
	v_cndmask_b32_e64 v84, v84, v175, s[0:1]
	s_and_b64 s[0:1], s[0:1], s[40:41]
	v_cndmask_b32_e64 v66, v66, v175, s[88:89]
	v_readlane_b32 s88, v242, 2
	s_and_b64 vcc, s[0:1], vcc
	v_cndmask_b32_e64 v69, v69, v175, s[94:95]
	v_cndmask_b32_e64 v68, v68, v175, s[92:93]
	s_movk_i32 s93, 0x6018
	s_mov_b32 s92, 0xf800000
	v_cndmask_b32_e64 v67, v67, v175, s[90:91]
	s_mov_b64 s[90:91], s[16:17]
	v_readlane_b32 s89, v242, 3
	v_cndmask_b32_e64 v73, v73, v175, s[86:87]
	v_readlane_b32 s86, v242, 0
	v_cndmask_b32_e64 v72, v72, v175, s[84:85]
	v_cndmask_b32_e64 v71, v71, v175, s[82:83]
	s_movk_i32 s83, 0x6000
	v_cndmask_b32_e64 v70, v70, v175, s[80:81]
	v_cndmask_b32_e64 v77, v77, v175, s[78:79]
	v_cndmask_b32_e64 v76, v76, v175, s[76:77]
	v_cndmask_b32_e64 v75, v75, v175, s[74:75]
	v_cndmask_b32_e64 v74, v74, v175, s[72:73]
	v_cndmask_b32_e64 v79, v79, v175, s[70:71]
	v_cndmask_b32_e64 v78, v78, v175, s[68:69]
	v_cndmask_b32_e64 v81, v81, v175, s[2:3]
	s_mov_b32 s56, s30
	v_cndmask_b32_e64 v83, v83, v175, s[0:1]
	v_cndmask_b32_e32 v82, v82, v175, vcc
	v_readlane_b32 s87, v242, 1

.Lmskip_fox_6:
	s_and_saveexec_b64 s[0:1], s[38:39]
	v_add_f32_e32 v1, v1, v114
	v_fmac_f32_e32 v1, v162, v146
	v_add_f32_e32 v66, v66, v67
	v_fmac_f32_e32 v66, v1, v96
	ds_write_b32 v185, v66
	s_or_b64 exec, exec, s[0:1]
	s_waitcnt lgkmcnt(0)
	ds_read_b128 v[78:81], v184
	ds_read_b128 v[74:77], v184 offset:32
	ds_read_b128 v[70:73], v184 offset:64
	ds_read_b128 v[66:69], v184 offset:96
	s_lshl_b32 s0, s5, 13
	s_waitcnt lgkmcnt(3)
	v_and_b32_e32 v1, 1, v180
	s_add_i32 s2, s0, 0
	v_cmp_eq_u32_e32 vcc, 0, v1
	v_lshlrev_b32_e32 v1, 10, v181
	v_lshlrev_b32_e32 v82, 1, v182
	v_add3_u32 v1, s2, v1, v82
	s_waitcnt lgkmcnt(0)
	s_barrier
	v_rcp_f32_e32 v66, v66
	v_rcp_f32_e32 v67, v67
	v_rcp_f32_e32 v68, v68
	v_rcp_f32_e32 v69, v69
	v_rcp_f32_e32 v70, v70
	v_rcp_f32_e32 v71, v71
	v_rcp_f32_e32 v72, v72
	v_rcp_f32_e32 v73, v73
	v_rcp_f32_e32 v74, v74
	v_rcp_f32_e32 v75, v75
	v_rcp_f32_e32 v76, v76
	v_rcp_f32_e32 v77, v77
	v_rcp_f32_e32 v78, v78
	v_rcp_f32_e32 v79, v79
	v_rcp_f32_e32 v80, v80
	v_rcp_f32_e32 v81, v81
	s_nop 1
	v_mul_f32_dpp v82, v50, v78 quad_perm:[1,0,3,2] row_mask:0xf bank_mask:0xf bound_ctrl:1
	v_mul_f32_e32 v50, v50, v78
	v_cvt_pk_bf16_f32 v50, v50, v82
	v_mul_f32_dpp v82, v34, v78 quad_perm:[1,0,3,2] row_mask:0xf bank_mask:0xf bound_ctrl:1
	v_mul_f32_e32 v34, v34, v78
	v_cvt_pk_bf16_f32 v34, v34, v82
	v_mul_f32_dpp v82, v18, v78 quad_perm:[1,0,3,2] row_mask:0xf bank_mask:0xf bound_ctrl:1
	v_mul_f32_e32 v18, v18, v78
	v_cvt_pk_bf16_f32 v18, v18, v82
	v_mul_f32_dpp v82, v2, v78 quad_perm:[1,0,3,2] row_mask:0xf bank_mask:0xf bound_ctrl:1
	v_mul_f32_e32 v2, v2, v78
	v_cvt_pk_bf16_f32 v2, v2, v82
	v_mul_f32_dpp v82, v51, v79 quad_perm:[1,0,3,2] row_mask:0xf bank_mask:0xf bound_ctrl:1
	v_mul_f32_e32 v51, v51, v79
	v_cvt_pk_bf16_f32 v51, v51, v82
	v_mul_f32_dpp v82, v35, v79 quad_perm:[1,0,3,2] row_mask:0xf bank_mask:0xf bound_ctrl:1
	v_mul_f32_e32 v35, v35, v79
	v_cvt_pk_bf16_f32 v35, v35, v82
	v_mul_f32_dpp v82, v19, v79 quad_perm:[1,0,3,2] row_mask:0xf bank_mask:0xf bound_ctrl:1
	v_mul_f32_e32 v19, v19, v79
	v_cvt_pk_bf16_f32 v19, v19, v82
	v_mul_f32_dpp v82, v3, v79 quad_perm:[1,0,3,2] row_mask:0xf bank_mask:0xf bound_ctrl:1
	v_mul_f32_e32 v3, v3, v79
	v_cvt_pk_bf16_f32 v3, v3, v82
	v_mul_f32_dpp v82, v52, v80 quad_perm:[1,0,3,2] row_mask:0xf bank_mask:0xf bound_ctrl:1
	v_mul_f32_e32 v52, v52, v80
	v_cvt_pk_bf16_f32 v52, v52, v82
	v_mul_f32_dpp v82, v36, v80 quad_perm:[1,0,3,2] row_mask:0xf bank_mask:0xf bound_ctrl:1
	v_mul_f32_e32 v36, v36, v80
	v_cvt_pk_bf16_f32 v36, v36, v82
	v_mul_f32_dpp v82, v20, v80 quad_perm:[1,0,3,2] row_mask:0xf bank_mask:0xf bound_ctrl:1
	v_mul_f32_e32 v20, v20, v80
	v_cvt_pk_bf16_f32 v20, v20, v82
	v_mul_f32_dpp v82, v4, v80 quad_perm:[1,0,3,2] row_mask:0xf bank_mask:0xf bound_ctrl:1
	v_mul_f32_e32 v4, v4, v80
	v_cvt_pk_bf16_f32 v4, v4, v82
	v_mul_f32_dpp v82, v53, v81 quad_perm:[1,0,3,2] row_mask:0xf bank_mask:0xf bound_ctrl:1
	v_mul_f32_e32 v53, v53, v81
	v_cvt_pk_bf16_f32 v53, v53, v82
	v_mul_f32_dpp v82, v37, v81 quad_perm:[1,0,3,2] row_mask:0xf bank_mask:0xf bound_ctrl:1
	v_mul_f32_e32 v37, v37, v81
	v_cvt_pk_bf16_f32 v37, v37, v82
	v_mul_f32_dpp v82, v21, v81 quad_perm:[1,0,3,2] row_mask:0xf bank_mask:0xf bound_ctrl:1
	v_mul_f32_e32 v21, v21, v81
	v_cvt_pk_bf16_f32 v21, v21, v82
	v_mul_f32_dpp v82, v5, v81 quad_perm:[1,0,3,2] row_mask:0xf bank_mask:0xf bound_ctrl:1
	v_mul_f32_e32 v5, v5, v81
	v_cvt_pk_bf16_f32 v5, v5, v82
	v_mul_f32_dpp v82, v54, v74 quad_perm:[1,0,3,2] row_mask:0xf bank_mask:0xf bound_ctrl:1
	v_mul_f32_e32 v54, v54, v74
	v_cvt_pk_bf16_f32 v54, v54, v82
	v_mul_f32_dpp v82, v38, v74 quad_perm:[1,0,3,2] row_mask:0xf bank_mask:0xf bound_ctrl:1
	v_mul_f32_e32 v38, v38, v74
	v_cvt_pk_bf16_f32 v38, v38, v82
	v_mul_f32_dpp v82, v22, v74 quad_perm:[1,0,3,2] row_mask:0xf bank_mask:0xf bound_ctrl:1
	v_mul_f32_e32 v22, v22, v74
	v_cvt_pk_bf16_f32 v22, v22, v82
	v_mul_f32_dpp v82, v6, v74 quad_perm:[1,0,3,2] row_mask:0xf bank_mask:0xf bound_ctrl:1
	v_mul_f32_e32 v6, v6, v74
	v_cvt_pk_bf16_f32 v6, v6, v82
	v_mul_f32_dpp v82, v55, v75 quad_perm:[1,0,3,2] row_mask:0xf bank_mask:0xf bound_ctrl:1
	v_mul_f32_e32 v55, v55, v75
	v_cvt_pk_bf16_f32 v55, v55, v82
	v_mul_f32_dpp v82, v39, v75 quad_perm:[1,0,3,2] row_mask:0xf bank_mask:0xf bound_ctrl:1
	v_mul_f32_e32 v39, v39, v75
	v_cvt_pk_bf16_f32 v39, v39, v82
	v_mul_f32_dpp v82, v23, v75 quad_perm:[1,0,3,2] row_mask:0xf bank_mask:0xf bound_ctrl:1
	v_mul_f32_e32 v23, v23, v75
	v_cvt_pk_bf16_f32 v23, v23, v82
	v_mul_f32_dpp v82, v7, v75 quad_perm:[1,0,3,2] row_mask:0xf bank_mask:0xf bound_ctrl:1
	v_mul_f32_e32 v7, v7, v75
	v_cvt_pk_bf16_f32 v7, v7, v82
	v_mul_f32_dpp v82, v56, v76 quad_perm:[1,0,3,2] row_mask:0xf bank_mask:0xf bound_ctrl:1
	v_mul_f32_e32 v56, v56, v76
	v_cvt_pk_bf16_f32 v56, v56, v82
	v_mul_f32_dpp v82, v40, v76 quad_perm:[1,0,3,2] row_mask:0xf bank_mask:0xf bound_ctrl:1
	v_mul_f32_e32 v40, v40, v76
	v_cvt_pk_bf16_f32 v40, v40, v82
	v_mul_f32_dpp v82, v24, v76 quad_perm:[1,0,3,2] row_mask:0xf bank_mask:0xf bound_ctrl:1
	v_mul_f32_e32 v24, v24, v76
	v_cvt_pk_bf16_f32 v24, v24, v82
	v_mul_f32_dpp v82, v8, v76 quad_perm:[1,0,3,2] row_mask:0xf bank_mask:0xf bound_ctrl:1
	v_mul_f32_e32 v8, v8, v76
	v_cvt_pk_bf16_f32 v8, v8, v82
	v_mul_f32_dpp v82, v57, v77 quad_perm:[1,0,3,2] row_mask:0xf bank_mask:0xf bound_ctrl:1
	v_mul_f32_e32 v57, v57, v77
	v_cvt_pk_bf16_f32 v57, v57, v82
	v_mul_f32_dpp v82, v41, v77 quad_perm:[1,0,3,2] row_mask:0xf bank_mask:0xf bound_ctrl:1
	v_mul_f32_e32 v41, v41, v77
	v_cvt_pk_bf16_f32 v41, v41, v82
	v_mul_f32_dpp v82, v25, v77 quad_perm:[1,0,3,2] row_mask:0xf bank_mask:0xf bound_ctrl:1
	v_mul_f32_e32 v25, v25, v77
	v_cvt_pk_bf16_f32 v25, v25, v82
	v_mul_f32_dpp v82, v9, v77 quad_perm:[1,0,3,2] row_mask:0xf bank_mask:0xf bound_ctrl:1
	v_mul_f32_e32 v9, v9, v77
	v_cvt_pk_bf16_f32 v9, v9, v82
	v_mul_f32_dpp v82, v58, v70 quad_perm:[1,0,3,2] row_mask:0xf bank_mask:0xf bound_ctrl:1
	v_mul_f32_e32 v58, v58, v70
	v_cvt_pk_bf16_f32 v58, v58, v82
	v_mul_f32_dpp v82, v42, v70 quad_perm:[1,0,3,2] row_mask:0xf bank_mask:0xf bound_ctrl:1
	v_mul_f32_e32 v42, v42, v70
	v_cvt_pk_bf16_f32 v42, v42, v82
	v_mul_f32_dpp v82, v26, v70 quad_perm:[1,0,3,2] row_mask:0xf bank_mask:0xf bound_ctrl:1
	v_mul_f32_e32 v26, v26, v70
	v_cvt_pk_bf16_f32 v26, v26, v82
	v_mul_f32_dpp v82, v10, v70 quad_perm:[1,0,3,2] row_mask:0xf bank_mask:0xf bound_ctrl:1
	v_mul_f32_e32 v10, v10, v70
	v_cvt_pk_bf16_f32 v10, v10, v82
	v_mul_f32_dpp v82, v59, v71 quad_perm:[1,0,3,2] row_mask:0xf bank_mask:0xf bound_ctrl:1
	v_mul_f32_e32 v59, v59, v71
	v_cvt_pk_bf16_f32 v59, v59, v82
	v_mul_f32_dpp v82, v43, v71 quad_perm:[1,0,3,2] row_mask:0xf bank_mask:0xf bound_ctrl:1
	v_mul_f32_e32 v43, v43, v71
	v_cvt_pk_bf16_f32 v43, v43, v82
	v_mul_f32_dpp v82, v27, v71 quad_perm:[1,0,3,2] row_mask:0xf bank_mask:0xf bound_ctrl:1
	v_mul_f32_e32 v27, v27, v71
	v_cvt_pk_bf16_f32 v27, v27, v82
	v_mul_f32_dpp v82, v11, v71 quad_perm:[1,0,3,2] row_mask:0xf bank_mask:0xf bound_ctrl:1
	v_mul_f32_e32 v11, v11, v71
	v_cvt_pk_bf16_f32 v11, v11, v82
	v_mul_f32_dpp v82, v60, v72 quad_perm:[1,0,3,2] row_mask:0xf bank_mask:0xf bound_ctrl:1
	v_mul_f32_e32 v60, v60, v72
	v_cvt_pk_bf16_f32 v60, v60, v82
	v_mul_f32_dpp v82, v44, v72 quad_perm:[1,0,3,2] row_mask:0xf bank_mask:0xf bound_ctrl:1
	v_mul_f32_e32 v44, v44, v72
	v_cvt_pk_bf16_f32 v44, v44, v82
	v_mul_f32_dpp v82, v28, v72 quad_perm:[1,0,3,2] row_mask:0xf bank_mask:0xf bound_ctrl:1
	v_mul_f32_e32 v28, v28, v72
	v_cvt_pk_bf16_f32 v28, v28, v82
	v_mul_f32_dpp v82, v12, v72 quad_perm:[1,0,3,2] row_mask:0xf bank_mask:0xf bound_ctrl:1
	v_mul_f32_e32 v12, v12, v72
	v_cvt_pk_bf16_f32 v12, v12, v82
	v_mul_f32_dpp v82, v61, v73 quad_perm:[1,0,3,2] row_mask:0xf bank_mask:0xf bound_ctrl:1
	v_mul_f32_e32 v61, v61, v73
	v_cvt_pk_bf16_f32 v61, v61, v82
	v_mul_f32_dpp v82, v45, v73 quad_perm:[1,0,3,2] row_mask:0xf bank_mask:0xf bound_ctrl:1
	v_mul_f32_e32 v45, v45, v73
	v_cvt_pk_bf16_f32 v45, v45, v82
	v_mul_f32_dpp v82, v29, v73 quad_perm:[1,0,3,2] row_mask:0xf bank_mask:0xf bound_ctrl:1
	v_mul_f32_e32 v29, v29, v73
	v_cvt_pk_bf16_f32 v29, v29, v82
	v_mul_f32_dpp v82, v13, v73 quad_perm:[1,0,3,2] row_mask:0xf bank_mask:0xf bound_ctrl:1
	v_mul_f32_e32 v13, v13, v73
	v_cvt_pk_bf16_f32 v13, v13, v82
	v_mul_f32_dpp v82, v62, v66 quad_perm:[1,0,3,2] row_mask:0xf bank_mask:0xf bound_ctrl:1
	v_mul_f32_e32 v62, v62, v66
	v_cvt_pk_bf16_f32 v62, v62, v82
	v_mul_f32_dpp v82, v46, v66 quad_perm:[1,0,3,2] row_mask:0xf bank_mask:0xf bound_ctrl:1
	v_mul_f32_e32 v46, v46, v66
	v_cvt_pk_bf16_f32 v46, v46, v82
	v_mul_f32_dpp v82, v30, v66 quad_perm:[1,0,3,2] row_mask:0xf bank_mask:0xf bound_ctrl:1
	v_mul_f32_e32 v30, v30, v66
	v_cvt_pk_bf16_f32 v30, v30, v82
	v_mul_f32_dpp v82, v14, v66 quad_perm:[1,0,3,2] row_mask:0xf bank_mask:0xf bound_ctrl:1
	v_mul_f32_e32 v14, v14, v66
	v_cvt_pk_bf16_f32 v14, v14, v82
	v_mul_f32_dpp v82, v63, v67 quad_perm:[1,0,3,2] row_mask:0xf bank_mask:0xf bound_ctrl:1
	v_mul_f32_e32 v63, v63, v67
	v_cvt_pk_bf16_f32 v63, v63, v82
	v_mul_f32_dpp v82, v47, v67 quad_perm:[1,0,3,2] row_mask:0xf bank_mask:0xf bound_ctrl:1
	v_mul_f32_e32 v47, v47, v67
	v_cvt_pk_bf16_f32 v47, v47, v82
	v_mul_f32_dpp v82, v31, v67 quad_perm:[1,0,3,2] row_mask:0xf bank_mask:0xf bound_ctrl:1
	v_mul_f32_e32 v31, v31, v67
	v_cvt_pk_bf16_f32 v31, v31, v82
	v_mul_f32_dpp v82, v15, v67 quad_perm:[1,0,3,2] row_mask:0xf bank_mask:0xf bound_ctrl:1
	v_mul_f32_e32 v15, v15, v67
	v_cvt_pk_bf16_f32 v15, v15, v82
	v_mul_f32_dpp v82, v64, v68 quad_perm:[1,0,3,2] row_mask:0xf bank_mask:0xf bound_ctrl:1
	v_mul_f32_e32 v64, v64, v68
	v_cvt_pk_bf16_f32 v64, v64, v82
	v_mul_f32_dpp v82, v48, v68 quad_perm:[1,0,3,2] row_mask:0xf bank_mask:0xf bound_ctrl:1
	v_mul_f32_e32 v48, v48, v68
	v_cvt_pk_bf16_f32 v48, v48, v82
	v_mul_f32_dpp v82, v32, v68 quad_perm:[1,0,3,2] row_mask:0xf bank_mask:0xf bound_ctrl:1
	v_mul_f32_e32 v32, v32, v68
	v_cvt_pk_bf16_f32 v32, v32, v82
	v_mul_f32_dpp v82, v16, v68 quad_perm:[1,0,3,2] row_mask:0xf bank_mask:0xf bound_ctrl:1
	v_mul_f32_e32 v16, v16, v68
	v_cvt_pk_bf16_f32 v16, v16, v82
	v_mul_f32_dpp v82, v65, v69 quad_perm:[1,0,3,2] row_mask:0xf bank_mask:0xf bound_ctrl:1
	v_mul_f32_e32 v65, v65, v69
	v_cvt_pk_bf16_f32 v65, v65, v82
	v_mul_f32_dpp v82, v49, v69 quad_perm:[1,0,3,2] row_mask:0xf bank_mask:0xf bound_ctrl:1
	v_mul_f32_e32 v49, v49, v69
	v_cvt_pk_bf16_f32 v49, v49, v82
	v_mul_f32_dpp v82, v33, v69 quad_perm:[1,0,3,2] row_mask:0xf bank_mask:0xf bound_ctrl:1
	v_mul_f32_e32 v33, v33, v69
	v_cvt_pk_bf16_f32 v33, v33, v82
	v_mul_f32_dpp v82, v17, v69 quad_perm:[1,0,3,2] row_mask:0xf bank_mask:0xf bound_ctrl:1
	v_mul_f32_e32 v17, v17, v69
	v_cvt_pk_bf16_f32 v17, v17, v82
	s_and_saveexec_b64 s[0:1], vcc
	ds_write_b32 v1, v50
	ds_write_b32 v1, v34 offset:64
	ds_write_b32 v1, v18 offset:128
	ds_write_b32 v1, v2 offset:192
	ds_write_b32 v1, v51 offset:256
	ds_write_b32 v1, v35 offset:320
	ds_write_b32 v1, v19 offset:384
	ds_write_b32 v1, v3 offset:448
	ds_write_b32 v1, v52 offset:512
	ds_write_b32 v1, v36 offset:576
	ds_write_b32 v1, v20 offset:640
	ds_write_b32 v1, v4 offset:704
	ds_write_b32 v1, v53 offset:768
	ds_write_b32 v1, v37 offset:832
	ds_write_b32 v1, v21 offset:896
	ds_write_b32 v1, v5 offset:960
	ds_write_b32 v1, v54 offset:2048
	ds_write_b32 v1, v38 offset:2112
	ds_write_b32 v1, v22 offset:2176
	ds_write_b32 v1, v6 offset:2240
	ds_write_b32 v1, v55 offset:2304
	ds_write_b32 v1, v39 offset:2368
	ds_write_b32 v1, v23 offset:2432
	ds_write_b32 v1, v7 offset:2496
	ds_write_b32 v1, v56 offset:2560
	ds_write_b32 v1, v40 offset:2624
	ds_write_b32 v1, v24 offset:2688
	ds_write_b32 v1, v8 offset:2752
	ds_write_b32 v1, v57 offset:2816
	ds_write_b32 v1, v41 offset:2880
	ds_write_b32 v1, v25 offset:2944
	ds_write_b32 v1, v9 offset:3008
	ds_write_b32 v1, v58 offset:4096
	ds_write_b32 v1, v42 offset:4160
	ds_write_b32 v1, v26 offset:4224
	ds_write_b32 v1, v10 offset:4288
	ds_write_b32 v1, v59 offset:4352
	ds_write_b32 v1, v43 offset:4416
	ds_write_b32 v1, v27 offset:4480
	ds_write_b32 v1, v11 offset:4544
	ds_write_b32 v1, v60 offset:4608
	ds_write_b32 v1, v44 offset:4672
	ds_write_b32 v1, v28 offset:4736
	ds_write_b32 v1, v12 offset:4800
	ds_write_b32 v1, v61 offset:4864
	ds_write_b32 v1, v45 offset:4928
	ds_write_b32 v1, v29 offset:4992
	ds_write_b32 v1, v13 offset:5056
	ds_write_b32 v1, v62 offset:6144
	ds_write_b32 v1, v46 offset:6208
	ds_write_b32 v1, v30 offset:6272
	ds_write_b32 v1, v14 offset:6336
	ds_write_b32 v1, v63 offset:6400
	ds_write_b32 v1, v47 offset:6464
	ds_write_b32 v1, v31 offset:6528
	ds_write_b32 v1, v15 offset:6592
	ds_write_b32 v1, v64 offset:6656
	ds_write_b32 v1, v48 offset:6720
	ds_write_b32 v1, v32 offset:6784
	ds_write_b32 v1, v16 offset:6848
	ds_write_b32 v1, v65 offset:6912
	ds_write_b32 v1, v49 offset:6976
	ds_write_b32 v1, v33 offset:7040
	ds_write_b32 v1, v17 offset:7104
	s_or_b64 exec, exec, s[0:1]
	s_lshl_b64 s[0:1], s[96:97], 12
	v_readlane_b32 s8, v245, 30
	v_readlane_b32 s9, v245, 31
	s_add_u32 s0, s8, s0
	s_addc_u32 s1, s9, s1
	v_and_b32_e32 v162, 0xf0, v179
	s_add_u32 s3, s0, s34
	v_lshrrev_b32_e32 v1, 4, v169
	v_add_u32_e32 v10, s2, v162
	s_addc_u32 s8, s1, s35
	s_ashr_i32 s5, s4, 31
	s_waitcnt lgkmcnt(0)
	v_lshl_add_u32 v2, v1, 8, v10
	s_lshl_b64 s[0:1], s[4:5], 12
	ds_read_b128 v[2:5], v2
	s_add_u32 s0, s3, s0
	s_addc_u32 s1, s8, s1
	v_lshl_add_u64 v[6:7], s[0:1], 0, v[162:163]
	v_lshlrev_b32_e32 v162, 12, v1
	v_lshl_add_u64 v[8:9], v[6:7], 0, v[162:163]
	s_waitcnt lgkmcnt(0)
	global_store_dwordx4 v[8:9], v[2:5], off offset:2560
	v_or_b32_e32 v8, 4, v1
	v_lshlrev_b32_e32 v162, 12, v8
	v_lshl_add_u32 v2, v8, 8, v10
	ds_read_b128 v[2:5], v2
	v_lshl_add_u64 v[8:9], v[6:7], 0, v[162:163]
	s_waitcnt lgkmcnt(0)
	global_store_dwordx4 v[8:9], v[2:5], off offset:2560
	v_or_b32_e32 v8, 8, v1
	s_nop 0
	v_lshl_add_u32 v2, v8, 8, v10
	ds_read_b128 v[2:5], v2
	v_lshlrev_b32_e32 v162, 12, v8
	v_lshl_add_u64 v[8:9], v[6:7], 0, v[162:163]
	s_waitcnt lgkmcnt(0)
	global_store_dwordx4 v[8:9], v[2:5], off offset:2560
	v_or_b32_e32 v8, 12, v1
	s_nop 0
	v_lshl_add_u32 v2, v8, 8, v10
	ds_read_b128 v[2:5], v2
	v_lshlrev_b32_e32 v162, 12, v8
	v_lshl_add_u64 v[8:9], v[6:7], 0, v[162:163]
	s_waitcnt lgkmcnt(0)
	global_store_dwordx4 v[8:9], v[2:5], off offset:2560
	v_or_b32_e32 v8, 16, v1
	s_nop 0
	v_lshl_add_u32 v2, v8, 8, v10
	ds_read_b128 v[2:5], v2
	v_lshlrev_b32_e32 v162, 12, v8
	v_lshl_add_u64 v[8:9], v[6:7], 0, v[162:163]
	s_waitcnt lgkmcnt(0)
	global_store_dwordx4 v[8:9], v[2:5], off offset:2560
	v_or_b32_e32 v8, 20, v1
	s_nop 0
	v_lshl_add_u32 v2, v8, 8, v10
	ds_read_b128 v[2:5], v2
	v_lshlrev_b32_e32 v162, 12, v8
	v_lshl_add_u64 v[8:9], v[6:7], 0, v[162:163]
	s_waitcnt lgkmcnt(0)
	global_store_dwordx4 v[8:9], v[2:5], off offset:2560
	v_or_b32_e32 v8, 24, v1
	s_nop 0
	v_lshl_add_u32 v2, v8, 8, v10
	ds_read_b128 v[2:5], v2
	v_lshlrev_b32_e32 v162, 12, v8
	v_lshl_add_u64 v[8:9], v[6:7], 0, v[162:163]
	v_or_b32_e32 v1, 28, v1
	v_lshlrev_b32_e32 v162, 12, v1
	s_waitcnt lgkmcnt(0)
	global_store_dwordx4 v[8:9], v[2:5], off offset:2560
	v_lshl_add_u64 v[6:7], v[6:7], 0, v[162:163]
	s_nop 0
	v_lshl_add_u32 v2, v1, 8, v10
	ds_read_b128 v[2:5], v2
	s_waitcnt lgkmcnt(0)
	global_store_dwordx4 v[6:7], v[2:5], off offset:2560
	s_barrier
	s_and_saveexec_b64 s[0:1], s[36:37]
	s_cbranch_execz .LBB0_802
	v_readlane_b32 s2, v243, 55
	s_nop 1
	v_mov_b32_e32 v1, s2
	ds_write_b32 v1, v168

.Lmskip_dif_6:
	v_cmp_gt_u32_e32 vcc, 32, v149
	s_and_saveexec_b64 s[0:1], vcc
	v_add_f32_e32 v68, v98, v99
	v_fmac_f32_e32 v68, v157, v114
	v_add_f32_e32 v66, v66, v67
	v_fmac_f32_e32 v66, v68, v100
	ds_write_b32 v155, v66
	s_or_b64 exec, exec, s[0:1]
	s_waitcnt lgkmcnt(0)
	ds_read_b128 v[78:81], v154
	ds_read_b128 v[74:77], v154 offset:32
	ds_read_b128 v[70:73], v154 offset:64
	ds_read_b128 v[66:69], v154 offset:96
	s_lshl_b32 s0, s29, 13
	s_waitcnt lgkmcnt(3)
	v_rcp_f32_e32 v82, v78
	v_and_b32_e32 v78, 1, v150
	s_add_i32 s2, s0, 0
	v_cmp_eq_u32_e32 vcc, 0, v78
	v_lshlrev_b32_e32 v78, 10, v152
	v_lshlrev_b32_e32 v83, 1, v151
	v_add3_u32 v78, s2, v78, v83
	s_waitcnt lgkmcnt(0)
	s_barrier
	v_rcp_f32_e32 v66, v66
	v_rcp_f32_e32 v67, v67
	v_rcp_f32_e32 v68, v68
	v_rcp_f32_e32 v69, v69
	v_rcp_f32_e32 v70, v70
	v_rcp_f32_e32 v71, v71
	v_rcp_f32_e32 v72, v72
	v_rcp_f32_e32 v73, v73
	v_rcp_f32_e32 v74, v74
	v_rcp_f32_e32 v75, v75
	v_rcp_f32_e32 v76, v76
	v_rcp_f32_e32 v77, v77
	v_rcp_f32_e32 v79, v79
	v_rcp_f32_e32 v80, v80
	v_rcp_f32_e32 v81, v81
	s_nop 1
	v_mul_f32_dpp v83, v50, v82 quad_perm:[1,0,3,2] row_mask:0xf bank_mask:0xf bound_ctrl:1
	v_mul_f32_e32 v50, v50, v82
	v_cvt_pk_bf16_f32 v50, v50, v83
	v_mul_f32_dpp v83, v34, v82 quad_perm:[1,0,3,2] row_mask:0xf bank_mask:0xf bound_ctrl:1
	v_mul_f32_e32 v34, v34, v82
	v_cvt_pk_bf16_f32 v34, v34, v83
	v_mul_f32_dpp v83, v18, v82 quad_perm:[1,0,3,2] row_mask:0xf bank_mask:0xf bound_ctrl:1
	v_mul_f32_e32 v18, v18, v82
	v_cvt_pk_bf16_f32 v18, v18, v83
	v_mul_f32_dpp v83, v2, v82 quad_perm:[1,0,3,2] row_mask:0xf bank_mask:0xf bound_ctrl:1
	v_mul_f32_e32 v2, v2, v82
	v_cvt_pk_bf16_f32 v2, v2, v83
	v_mul_f32_dpp v83, v51, v79 quad_perm:[1,0,3,2] row_mask:0xf bank_mask:0xf bound_ctrl:1
	v_mul_f32_e32 v51, v51, v79
	v_cvt_pk_bf16_f32 v51, v51, v83
	v_mul_f32_dpp v83, v35, v79 quad_perm:[1,0,3,2] row_mask:0xf bank_mask:0xf bound_ctrl:1
	v_mul_f32_e32 v35, v35, v79
	v_cvt_pk_bf16_f32 v35, v35, v83
	v_mul_f32_dpp v83, v19, v79 quad_perm:[1,0,3,2] row_mask:0xf bank_mask:0xf bound_ctrl:1
	v_mul_f32_e32 v19, v19, v79
	v_cvt_pk_bf16_f32 v19, v19, v83
	v_mul_f32_dpp v83, v3, v79 quad_perm:[1,0,3,2] row_mask:0xf bank_mask:0xf bound_ctrl:1
	v_mul_f32_e32 v3, v3, v79
	v_cvt_pk_bf16_f32 v3, v3, v83
	v_mul_f32_dpp v83, v52, v80 quad_perm:[1,0,3,2] row_mask:0xf bank_mask:0xf bound_ctrl:1
	v_mul_f32_e32 v52, v52, v80
	v_cvt_pk_bf16_f32 v52, v52, v83
	v_mul_f32_dpp v83, v36, v80 quad_perm:[1,0,3,2] row_mask:0xf bank_mask:0xf bound_ctrl:1
	v_mul_f32_e32 v36, v36, v80
	v_cvt_pk_bf16_f32 v36, v36, v83
	v_mul_f32_dpp v83, v20, v80 quad_perm:[1,0,3,2] row_mask:0xf bank_mask:0xf bound_ctrl:1
	v_mul_f32_e32 v20, v20, v80
	v_cvt_pk_bf16_f32 v20, v20, v83
	v_mul_f32_dpp v83, v4, v80 quad_perm:[1,0,3,2] row_mask:0xf bank_mask:0xf bound_ctrl:1
	v_mul_f32_e32 v4, v4, v80
	v_cvt_pk_bf16_f32 v4, v4, v83
	v_mul_f32_dpp v83, v53, v81 quad_perm:[1,0,3,2] row_mask:0xf bank_mask:0xf bound_ctrl:1
	v_mul_f32_e32 v53, v53, v81
	v_cvt_pk_bf16_f32 v53, v53, v83
	v_mul_f32_dpp v83, v37, v81 quad_perm:[1,0,3,2] row_mask:0xf bank_mask:0xf bound_ctrl:1
	v_mul_f32_e32 v37, v37, v81
	v_cvt_pk_bf16_f32 v37, v37, v83
	v_mul_f32_dpp v83, v21, v81 quad_perm:[1,0,3,2] row_mask:0xf bank_mask:0xf bound_ctrl:1
	v_mul_f32_e32 v21, v21, v81
	v_cvt_pk_bf16_f32 v21, v21, v83
	v_mul_f32_dpp v83, v5, v81 quad_perm:[1,0,3,2] row_mask:0xf bank_mask:0xf bound_ctrl:1
	v_mul_f32_e32 v5, v5, v81
	v_cvt_pk_bf16_f32 v5, v5, v83
	v_mul_f32_dpp v83, v54, v74 quad_perm:[1,0,3,2] row_mask:0xf bank_mask:0xf bound_ctrl:1
	v_mul_f32_e32 v54, v54, v74
	v_cvt_pk_bf16_f32 v54, v54, v83
	v_mul_f32_dpp v83, v38, v74 quad_perm:[1,0,3,2] row_mask:0xf bank_mask:0xf bound_ctrl:1
	v_mul_f32_e32 v38, v38, v74
	v_cvt_pk_bf16_f32 v38, v38, v83
	v_mul_f32_dpp v83, v22, v74 quad_perm:[1,0,3,2] row_mask:0xf bank_mask:0xf bound_ctrl:1
	v_mul_f32_e32 v22, v22, v74
	v_cvt_pk_bf16_f32 v22, v22, v83
	v_mul_f32_dpp v83, v6, v74 quad_perm:[1,0,3,2] row_mask:0xf bank_mask:0xf bound_ctrl:1
	v_mul_f32_e32 v6, v6, v74
	v_cvt_pk_bf16_f32 v6, v6, v83
	v_mul_f32_dpp v83, v55, v75 quad_perm:[1,0,3,2] row_mask:0xf bank_mask:0xf bound_ctrl:1
	v_mul_f32_e32 v55, v55, v75
	v_cvt_pk_bf16_f32 v55, v55, v83
	v_mul_f32_dpp v83, v39, v75 quad_perm:[1,0,3,2] row_mask:0xf bank_mask:0xf bound_ctrl:1
	v_mul_f32_e32 v39, v39, v75
	v_cvt_pk_bf16_f32 v39, v39, v83
	v_mul_f32_dpp v83, v23, v75 quad_perm:[1,0,3,2] row_mask:0xf bank_mask:0xf bound_ctrl:1
	v_mul_f32_e32 v23, v23, v75
	v_cvt_pk_bf16_f32 v23, v23, v83
	v_mul_f32_dpp v83, v7, v75 quad_perm:[1,0,3,2] row_mask:0xf bank_mask:0xf bound_ctrl:1
	v_mul_f32_e32 v7, v7, v75
	v_cvt_pk_bf16_f32 v7, v7, v83
	v_mul_f32_dpp v83, v56, v76 quad_perm:[1,0,3,2] row_mask:0xf bank_mask:0xf bound_ctrl:1
	v_mul_f32_e32 v56, v56, v76
	v_cvt_pk_bf16_f32 v56, v56, v83
	v_mul_f32_dpp v83, v40, v76 quad_perm:[1,0,3,2] row_mask:0xf bank_mask:0xf bound_ctrl:1
	v_mul_f32_e32 v40, v40, v76
	v_cvt_pk_bf16_f32 v40, v40, v83
	v_mul_f32_dpp v83, v24, v76 quad_perm:[1,0,3,2] row_mask:0xf bank_mask:0xf bound_ctrl:1
	v_mul_f32_e32 v24, v24, v76
	v_cvt_pk_bf16_f32 v24, v24, v83
	v_mul_f32_dpp v83, v8, v76 quad_perm:[1,0,3,2] row_mask:0xf bank_mask:0xf bound_ctrl:1
	v_mul_f32_e32 v8, v8, v76
	v_cvt_pk_bf16_f32 v8, v8, v83
	v_mul_f32_dpp v83, v57, v77 quad_perm:[1,0,3,2] row_mask:0xf bank_mask:0xf bound_ctrl:1
	v_mul_f32_e32 v57, v57, v77
	v_cvt_pk_bf16_f32 v57, v57, v83
	v_mul_f32_dpp v83, v41, v77 quad_perm:[1,0,3,2] row_mask:0xf bank_mask:0xf bound_ctrl:1
	v_mul_f32_e32 v41, v41, v77
	v_cvt_pk_bf16_f32 v41, v41, v83
	v_mul_f32_dpp v83, v25, v77 quad_perm:[1,0,3,2] row_mask:0xf bank_mask:0xf bound_ctrl:1
	v_mul_f32_e32 v25, v25, v77
	v_cvt_pk_bf16_f32 v25, v25, v83
	v_mul_f32_dpp v83, v9, v77 quad_perm:[1,0,3,2] row_mask:0xf bank_mask:0xf bound_ctrl:1
	v_mul_f32_e32 v9, v9, v77
	v_cvt_pk_bf16_f32 v9, v9, v83
	v_mul_f32_dpp v83, v58, v70 quad_perm:[1,0,3,2] row_mask:0xf bank_mask:0xf bound_ctrl:1
	v_mul_f32_e32 v58, v58, v70
	v_cvt_pk_bf16_f32 v58, v58, v83
	v_mul_f32_dpp v83, v42, v70 quad_perm:[1,0,3,2] row_mask:0xf bank_mask:0xf bound_ctrl:1
	v_mul_f32_e32 v42, v42, v70
	v_cvt_pk_bf16_f32 v42, v42, v83
	v_mul_f32_dpp v83, v26, v70 quad_perm:[1,0,3,2] row_mask:0xf bank_mask:0xf bound_ctrl:1
	v_mul_f32_e32 v26, v26, v70
	v_cvt_pk_bf16_f32 v26, v26, v83
	v_mul_f32_dpp v83, v10, v70 quad_perm:[1,0,3,2] row_mask:0xf bank_mask:0xf bound_ctrl:1
	v_mul_f32_e32 v10, v10, v70
	v_cvt_pk_bf16_f32 v10, v10, v83
	v_mul_f32_dpp v83, v59, v71 quad_perm:[1,0,3,2] row_mask:0xf bank_mask:0xf bound_ctrl:1
	v_mul_f32_e32 v59, v59, v71
	v_cvt_pk_bf16_f32 v59, v59, v83
	v_mul_f32_dpp v83, v43, v71 quad_perm:[1,0,3,2] row_mask:0xf bank_mask:0xf bound_ctrl:1
	v_mul_f32_e32 v43, v43, v71
	v_cvt_pk_bf16_f32 v43, v43, v83
	v_mul_f32_dpp v83, v27, v71 quad_perm:[1,0,3,2] row_mask:0xf bank_mask:0xf bound_ctrl:1
	v_mul_f32_e32 v27, v27, v71
	v_cvt_pk_bf16_f32 v27, v27, v83
	v_mul_f32_dpp v83, v11, v71 quad_perm:[1,0,3,2] row_mask:0xf bank_mask:0xf bound_ctrl:1
	v_mul_f32_e32 v11, v11, v71
	v_cvt_pk_bf16_f32 v11, v11, v83
	v_mul_f32_dpp v83, v60, v72 quad_perm:[1,0,3,2] row_mask:0xf bank_mask:0xf bound_ctrl:1
	v_mul_f32_e32 v60, v60, v72
	v_cvt_pk_bf16_f32 v60, v60, v83
	v_mul_f32_dpp v83, v44, v72 quad_perm:[1,0,3,2] row_mask:0xf bank_mask:0xf bound_ctrl:1
	v_mul_f32_e32 v44, v44, v72
	v_cvt_pk_bf16_f32 v44, v44, v83
	v_mul_f32_dpp v83, v28, v72 quad_perm:[1,0,3,2] row_mask:0xf bank_mask:0xf bound_ctrl:1
	v_mul_f32_e32 v28, v28, v72
	v_cvt_pk_bf16_f32 v28, v28, v83
	v_mul_f32_dpp v83, v12, v72 quad_perm:[1,0,3,2] row_mask:0xf bank_mask:0xf bound_ctrl:1
	v_mul_f32_e32 v12, v12, v72
	v_cvt_pk_bf16_f32 v12, v12, v83
	v_mul_f32_dpp v83, v61, v73 quad_perm:[1,0,3,2] row_mask:0xf bank_mask:0xf bound_ctrl:1
	v_mul_f32_e32 v61, v61, v73
	v_cvt_pk_bf16_f32 v61, v61, v83
	v_mul_f32_dpp v83, v45, v73 quad_perm:[1,0,3,2] row_mask:0xf bank_mask:0xf bound_ctrl:1
	v_mul_f32_e32 v45, v45, v73
	v_cvt_pk_bf16_f32 v45, v45, v83
	v_mul_f32_dpp v83, v29, v73 quad_perm:[1,0,3,2] row_mask:0xf bank_mask:0xf bound_ctrl:1
	v_mul_f32_e32 v29, v29, v73
	v_cvt_pk_bf16_f32 v29, v29, v83
	v_mul_f32_dpp v83, v13, v73 quad_perm:[1,0,3,2] row_mask:0xf bank_mask:0xf bound_ctrl:1
	v_mul_f32_e32 v13, v13, v73
	v_cvt_pk_bf16_f32 v13, v13, v83
	v_mul_f32_dpp v83, v62, v66 quad_perm:[1,0,3,2] row_mask:0xf bank_mask:0xf bound_ctrl:1
	v_mul_f32_e32 v62, v62, v66
	v_cvt_pk_bf16_f32 v62, v62, v83
	v_mul_f32_dpp v83, v46, v66 quad_perm:[1,0,3,2] row_mask:0xf bank_mask:0xf bound_ctrl:1
	v_mul_f32_e32 v46, v46, v66
	v_cvt_pk_bf16_f32 v46, v46, v83
	v_mul_f32_dpp v83, v30, v66 quad_perm:[1,0,3,2] row_mask:0xf bank_mask:0xf bound_ctrl:1
	v_mul_f32_e32 v30, v30, v66
	v_cvt_pk_bf16_f32 v30, v30, v83
	v_mul_f32_dpp v83, v14, v66 quad_perm:[1,0,3,2] row_mask:0xf bank_mask:0xf bound_ctrl:1
	v_mul_f32_e32 v14, v14, v66
	v_cvt_pk_bf16_f32 v14, v14, v83
	v_mul_f32_dpp v83, v63, v67 quad_perm:[1,0,3,2] row_mask:0xf bank_mask:0xf bound_ctrl:1
	v_mul_f32_e32 v63, v63, v67
	v_cvt_pk_bf16_f32 v63, v63, v83
	v_mul_f32_dpp v83, v47, v67 quad_perm:[1,0,3,2] row_mask:0xf bank_mask:0xf bound_ctrl:1
	v_mul_f32_e32 v47, v47, v67
	v_cvt_pk_bf16_f32 v47, v47, v83
	v_mul_f32_dpp v83, v31, v67 quad_perm:[1,0,3,2] row_mask:0xf bank_mask:0xf bound_ctrl:1
	v_mul_f32_e32 v31, v31, v67
	v_cvt_pk_bf16_f32 v31, v31, v83
	v_mul_f32_dpp v83, v15, v67 quad_perm:[1,0,3,2] row_mask:0xf bank_mask:0xf bound_ctrl:1
	v_mul_f32_e32 v15, v15, v67
	v_cvt_pk_bf16_f32 v15, v15, v83
	v_mul_f32_dpp v83, v64, v68 quad_perm:[1,0,3,2] row_mask:0xf bank_mask:0xf bound_ctrl:1
	v_mul_f32_e32 v64, v64, v68
	v_cvt_pk_bf16_f32 v64, v64, v83
	v_mul_f32_dpp v83, v48, v68 quad_perm:[1,0,3,2] row_mask:0xf bank_mask:0xf bound_ctrl:1
	v_mul_f32_e32 v48, v48, v68
	v_cvt_pk_bf16_f32 v48, v48, v83
	v_mul_f32_dpp v83, v32, v68 quad_perm:[1,0,3,2] row_mask:0xf bank_mask:0xf bound_ctrl:1
	v_mul_f32_e32 v32, v32, v68
	v_cvt_pk_bf16_f32 v32, v32, v83
	v_mul_f32_dpp v83, v16, v68 quad_perm:[1,0,3,2] row_mask:0xf bank_mask:0xf bound_ctrl:1
	v_mul_f32_e32 v16, v16, v68
	v_cvt_pk_bf16_f32 v16, v16, v83
	v_mul_f32_dpp v83, v65, v69 quad_perm:[1,0,3,2] row_mask:0xf bank_mask:0xf bound_ctrl:1
	v_mul_f32_e32 v65, v65, v69
	v_cvt_pk_bf16_f32 v65, v65, v83
	v_mul_f32_dpp v83, v49, v69 quad_perm:[1,0,3,2] row_mask:0xf bank_mask:0xf bound_ctrl:1
	v_mul_f32_e32 v49, v49, v69
	v_cvt_pk_bf16_f32 v49, v49, v83
	v_mul_f32_dpp v83, v33, v69 quad_perm:[1,0,3,2] row_mask:0xf bank_mask:0xf bound_ctrl:1
	v_mul_f32_e32 v33, v33, v69
	v_cvt_pk_bf16_f32 v33, v33, v83
	v_mul_f32_dpp v83, v17, v69 quad_perm:[1,0,3,2] row_mask:0xf bank_mask:0xf bound_ctrl:1
	v_mul_f32_e32 v17, v17, v69
	v_cvt_pk_bf16_f32 v17, v17, v83
	s_and_saveexec_b64 s[0:1], vcc
	ds_write_b32 v78, v50
	ds_write_b32 v78, v34 offset:64
	ds_write_b32 v78, v18 offset:128
	ds_write_b32 v78, v2 offset:192
	ds_write_b32 v78, v51 offset:256
	ds_write_b32 v78, v35 offset:320
	ds_write_b32 v78, v19 offset:384
	ds_write_b32 v78, v3 offset:448
	ds_write_b32 v78, v52 offset:512
	ds_write_b32 v78, v36 offset:576
	ds_write_b32 v78, v20 offset:640
	ds_write_b32 v78, v4 offset:704
	ds_write_b32 v78, v53 offset:768
	ds_write_b32 v78, v37 offset:832
	ds_write_b32 v78, v21 offset:896
	ds_write_b32 v78, v5 offset:960
	ds_write_b32 v78, v54 offset:2048
	ds_write_b32 v78, v38 offset:2112
	ds_write_b32 v78, v22 offset:2176
	ds_write_b32 v78, v6 offset:2240
	ds_write_b32 v78, v55 offset:2304
	ds_write_b32 v78, v39 offset:2368
	ds_write_b32 v78, v23 offset:2432
	ds_write_b32 v78, v7 offset:2496
	ds_write_b32 v78, v56 offset:2560
	ds_write_b32 v78, v40 offset:2624
	ds_write_b32 v78, v24 offset:2688
	ds_write_b32 v78, v8 offset:2752
	ds_write_b32 v78, v57 offset:2816
	ds_write_b32 v78, v41 offset:2880
	ds_write_b32 v78, v25 offset:2944
	ds_write_b32 v78, v9 offset:3008
	ds_write_b32 v78, v58 offset:4096
	ds_write_b32 v78, v42 offset:4160
	ds_write_b32 v78, v26 offset:4224
	ds_write_b32 v78, v10 offset:4288
	ds_write_b32 v78, v59 offset:4352
	ds_write_b32 v78, v43 offset:4416
	ds_write_b32 v78, v27 offset:4480
	ds_write_b32 v78, v11 offset:4544
	ds_write_b32 v78, v60 offset:4608
	ds_write_b32 v78, v44 offset:4672
	ds_write_b32 v78, v28 offset:4736
	ds_write_b32 v78, v12 offset:4800
	ds_write_b32 v78, v61 offset:4864
	ds_write_b32 v78, v45 offset:4928
	ds_write_b32 v78, v29 offset:4992
	ds_write_b32 v78, v13 offset:5056
	ds_write_b32 v78, v62 offset:6144
	ds_write_b32 v78, v46 offset:6208
	ds_write_b32 v78, v30 offset:6272
	ds_write_b32 v78, v14 offset:6336
	ds_write_b32 v78, v63 offset:6400
	ds_write_b32 v78, v47 offset:6464
	ds_write_b32 v78, v31 offset:6528
	ds_write_b32 v78, v15 offset:6592
	ds_write_b32 v78, v64 offset:6656
	ds_write_b32 v78, v48 offset:6720
	ds_write_b32 v78, v32 offset:6784
	ds_write_b32 v78, v16 offset:6848
	ds_write_b32 v78, v65 offset:6912
	ds_write_b32 v78, v49 offset:6976
	ds_write_b32 v78, v33 offset:7040
	ds_write_b32 v78, v17 offset:7104
	s_or_b64 exec, exec, s[0:1]
	s_lshl_b64 s[0:1], s[18:19], 11
	v_readlane_b32 s8, v245, 32
	v_readlane_b32 s9, v245, 33
	s_add_u32 s3, s8, s0
	s_addc_u32 s8, s9, s1
	s_lshl_b32 s0, s28, 7
	s_ashr_i32 s1, s0, 31
	s_lshl_b64 s[0:1], s[0:1], 1
	v_and_b32_e32 v162, 0xf0, v148
	s_add_u32 s3, s3, s0
	v_lshrrev_b32_e32 v10, 4, v149
	v_add_u32_e32 v11, s2, v162
	s_addc_u32 s8, s8, s1
	s_ashr_i32 s35, s34, 31
	s_waitcnt lgkmcnt(0)
	v_lshl_add_u32 v2, v10, 8, v11
	s_lshl_b64 s[0:1], s[34:35], 11
	ds_read_b128 v[2:5], v2
	s_add_u32 s0, s3, s0
	s_addc_u32 s1, s8, s1
	v_lshl_add_u64 v[6:7], s[0:1], 0, v[162:163]
	v_lshlrev_b32_e32 v162, 11, v10
	v_lshl_add_u64 v[8:9], v[6:7], 0, v[162:163]
	s_waitcnt lgkmcnt(0)
	global_store_dwordx4 v[8:9], v[2:5], off
	v_or_b32_e32 v8, 4, v10
	v_lshlrev_b32_e32 v162, 11, v8
	v_lshl_add_u32 v2, v8, 8, v11
	ds_read_b128 v[2:5], v2
	v_lshl_add_u64 v[8:9], v[6:7], 0, v[162:163]
	s_waitcnt lgkmcnt(0)
	global_store_dwordx4 v[8:9], v[2:5], off
	v_or_b32_e32 v8, 8, v10
	s_nop 0
	v_lshl_add_u32 v2, v8, 8, v11
	ds_read_b128 v[2:5], v2
	v_lshlrev_b32_e32 v162, 11, v8
	v_lshl_add_u64 v[8:9], v[6:7], 0, v[162:163]
	s_waitcnt lgkmcnt(0)
	global_store_dwordx4 v[8:9], v[2:5], off
	v_or_b32_e32 v8, 12, v10
	s_nop 0
	v_lshl_add_u32 v2, v8, 8, v11
	ds_read_b128 v[2:5], v2
	v_lshlrev_b32_e32 v162, 11, v8
	v_lshl_add_u64 v[8:9], v[6:7], 0, v[162:163]
	s_waitcnt lgkmcnt(0)
	global_store_dwordx4 v[8:9], v[2:5], off
	v_or_b32_e32 v8, 16, v10
	s_nop 0
	v_lshl_add_u32 v2, v8, 8, v11
	ds_read_b128 v[2:5], v2
	v_lshlrev_b32_e32 v162, 11, v8
	v_lshl_add_u64 v[8:9], v[6:7], 0, v[162:163]
	s_waitcnt lgkmcnt(0)
	global_store_dwordx4 v[8:9], v[2:5], off
	v_or_b32_e32 v8, 20, v10
	s_nop 0
	v_lshl_add_u32 v2, v8, 8, v11
	ds_read_b128 v[2:5], v2
	v_lshlrev_b32_e32 v162, 11, v8
	v_lshl_add_u64 v[8:9], v[6:7], 0, v[162:163]
	s_waitcnt lgkmcnt(0)
	global_store_dwordx4 v[8:9], v[2:5], off
	v_or_b32_e32 v8, 24, v10
	s_nop 0
	v_lshl_add_u32 v2, v8, 8, v11
	ds_read_b128 v[2:5], v2
	v_lshlrev_b32_e32 v162, 11, v8
	v_lshl_add_u64 v[8:9], v[6:7], 0, v[162:163]
	s_waitcnt lgkmcnt(0)
	global_store_dwordx4 v[8:9], v[2:5], off
	v_or_b32_e32 v8, 28, v10
	s_nop 0
	v_lshl_add_u32 v2, v8, 8, v11
	ds_read_b128 v[2:5], v2
	v_lshlrev_b32_e32 v162, 11, v8
	v_lshl_add_u64 v[6:7], v[6:7], 0, v[162:163]
	s_waitcnt lgkmcnt(0)
	global_store_dwordx4 v[6:7], v[2:5], off
	s_barrier
	s_and_saveexec_b64 s[0:1], s[36:37]
	s_cbranch_execz .LBB0_814
	v_readlane_b32 s2, v243, 55
	s_nop 1
	v_mov_b32_e32 v2, s2
	ds_write_b32 v2, v1
	s_branch .LBB0_814

.LBB0_1428:
	s_or_b64 exec, exec, s[4:5]
	s_waitcnt lgkmcnt(0)
	v_add_u32_e32 v66, s42, v162
	ds_read_b128 v[78:81], v66
	ds_read_b128 v[74:77], v66 offset:32
	ds_read_b128 v[70:73], v66 offset:64
	ds_read_b128 v[66:69], v66 offset:96
	s_lshl_b32 s4, s35, 13
	s_waitcnt lgkmcnt(3)
	v_rcp_f32_e32 v82, v78
	v_and_b32_e32 v78, 1, v155
	s_add_i32 s8, s4, 0
	v_cmp_eq_u32_e32 vcc, 0, v78
	v_lshlrev_b32_e32 v78, 10, v157
	v_lshlrev_b32_e32 v83, 1, v156
	v_add3_u32 v78, s8, v78, v83
	s_waitcnt lgkmcnt(0)
	s_barrier
	v_rcp_f32_e32 v66, v66
	v_rcp_f32_e32 v67, v67
	v_rcp_f32_e32 v68, v68
	v_rcp_f32_e32 v69, v69
	v_rcp_f32_e32 v70, v70
	v_rcp_f32_e32 v71, v71
	v_rcp_f32_e32 v72, v72
	v_rcp_f32_e32 v73, v73
	v_rcp_f32_e32 v74, v74
	v_rcp_f32_e32 v75, v75
	v_rcp_f32_e32 v76, v76
	v_rcp_f32_e32 v77, v77
	v_rcp_f32_e32 v79, v79
	v_rcp_f32_e32 v80, v80
	v_rcp_f32_e32 v81, v81
	s_nop 1
	v_mul_f32_dpp v83, v2, v82 quad_perm:[1,0,3,2] row_mask:0xf bank_mask:0xf bound_ctrl:1
	v_mul_f32_e32 v2, v2, v82
	v_cvt_pk_bf16_f32 v2, v2, v83
	v_mul_f32_dpp v83, v18, v82 quad_perm:[1,0,3,2] row_mask:0xf bank_mask:0xf bound_ctrl:1
	v_mul_f32_e32 v18, v18, v82
	v_cvt_pk_bf16_f32 v18, v18, v83
	v_mul_f32_dpp v83, v34, v82 quad_perm:[1,0,3,2] row_mask:0xf bank_mask:0xf bound_ctrl:1
	v_mul_f32_e32 v34, v34, v82
	v_cvt_pk_bf16_f32 v34, v34, v83
	v_mul_f32_dpp v83, v50, v82 quad_perm:[1,0,3,2] row_mask:0xf bank_mask:0xf bound_ctrl:1
	v_mul_f32_e32 v50, v50, v82
	v_cvt_pk_bf16_f32 v50, v50, v83
	v_mul_f32_dpp v83, v3, v79 quad_perm:[1,0,3,2] row_mask:0xf bank_mask:0xf bound_ctrl:1
	v_mul_f32_e32 v3, v3, v79
	v_cvt_pk_bf16_f32 v3, v3, v83
	v_mul_f32_dpp v83, v19, v79 quad_perm:[1,0,3,2] row_mask:0xf bank_mask:0xf bound_ctrl:1
	v_mul_f32_e32 v19, v19, v79
	v_cvt_pk_bf16_f32 v19, v19, v83
	v_mul_f32_dpp v83, v35, v79 quad_perm:[1,0,3,2] row_mask:0xf bank_mask:0xf bound_ctrl:1
	v_mul_f32_e32 v35, v35, v79
	v_cvt_pk_bf16_f32 v35, v35, v83
	v_mul_f32_dpp v83, v51, v79 quad_perm:[1,0,3,2] row_mask:0xf bank_mask:0xf bound_ctrl:1
	v_mul_f32_e32 v51, v51, v79
	v_cvt_pk_bf16_f32 v51, v51, v83
	v_mul_f32_dpp v83, v4, v80 quad_perm:[1,0,3,2] row_mask:0xf bank_mask:0xf bound_ctrl:1
	v_mul_f32_e32 v4, v4, v80
	v_cvt_pk_bf16_f32 v4, v4, v83
	v_mul_f32_dpp v83, v20, v80 quad_perm:[1,0,3,2] row_mask:0xf bank_mask:0xf bound_ctrl:1
	v_mul_f32_e32 v20, v20, v80
	v_cvt_pk_bf16_f32 v20, v20, v83
	v_mul_f32_dpp v83, v36, v80 quad_perm:[1,0,3,2] row_mask:0xf bank_mask:0xf bound_ctrl:1
	v_mul_f32_e32 v36, v36, v80
	v_cvt_pk_bf16_f32 v36, v36, v83
	v_mul_f32_dpp v83, v52, v80 quad_perm:[1,0,3,2] row_mask:0xf bank_mask:0xf bound_ctrl:1
	v_mul_f32_e32 v52, v52, v80
	v_cvt_pk_bf16_f32 v52, v52, v83
	v_mul_f32_dpp v83, v5, v81 quad_perm:[1,0,3,2] row_mask:0xf bank_mask:0xf bound_ctrl:1
	v_mul_f32_e32 v5, v5, v81
	v_cvt_pk_bf16_f32 v5, v5, v83
	v_mul_f32_dpp v83, v21, v81 quad_perm:[1,0,3,2] row_mask:0xf bank_mask:0xf bound_ctrl:1
	v_mul_f32_e32 v21, v21, v81
	v_cvt_pk_bf16_f32 v21, v21, v83
	v_mul_f32_dpp v83, v37, v81 quad_perm:[1,0,3,2] row_mask:0xf bank_mask:0xf bound_ctrl:1
	v_mul_f32_e32 v37, v37, v81
	v_cvt_pk_bf16_f32 v37, v37, v83
	v_mul_f32_dpp v83, v53, v81 quad_perm:[1,0,3,2] row_mask:0xf bank_mask:0xf bound_ctrl:1
	v_mul_f32_e32 v53, v53, v81
	v_cvt_pk_bf16_f32 v53, v53, v83
	v_mul_f32_dpp v83, v6, v74 quad_perm:[1,0,3,2] row_mask:0xf bank_mask:0xf bound_ctrl:1
	v_mul_f32_e32 v6, v6, v74
	v_cvt_pk_bf16_f32 v6, v6, v83
	v_mul_f32_dpp v83, v22, v74 quad_perm:[1,0,3,2] row_mask:0xf bank_mask:0xf bound_ctrl:1
	v_mul_f32_e32 v22, v22, v74
	v_cvt_pk_bf16_f32 v22, v22, v83
	v_mul_f32_dpp v83, v38, v74 quad_perm:[1,0,3,2] row_mask:0xf bank_mask:0xf bound_ctrl:1
	v_mul_f32_e32 v38, v38, v74
	v_cvt_pk_bf16_f32 v38, v38, v83
	v_mul_f32_dpp v83, v54, v74 quad_perm:[1,0,3,2] row_mask:0xf bank_mask:0xf bound_ctrl:1
	v_mul_f32_e32 v54, v54, v74
	v_cvt_pk_bf16_f32 v54, v54, v83
	v_mul_f32_dpp v83, v7, v75 quad_perm:[1,0,3,2] row_mask:0xf bank_mask:0xf bound_ctrl:1
	v_mul_f32_e32 v7, v7, v75
	v_cvt_pk_bf16_f32 v7, v7, v83
	v_mul_f32_dpp v83, v23, v75 quad_perm:[1,0,3,2] row_mask:0xf bank_mask:0xf bound_ctrl:1
	v_mul_f32_e32 v23, v23, v75
	v_cvt_pk_bf16_f32 v23, v23, v83
	v_mul_f32_dpp v83, v39, v75 quad_perm:[1,0,3,2] row_mask:0xf bank_mask:0xf bound_ctrl:1
	v_mul_f32_e32 v39, v39, v75
	v_cvt_pk_bf16_f32 v39, v39, v83
	v_mul_f32_dpp v83, v55, v75 quad_perm:[1,0,3,2] row_mask:0xf bank_mask:0xf bound_ctrl:1
	v_mul_f32_e32 v55, v55, v75
	v_cvt_pk_bf16_f32 v55, v55, v83
	v_mul_f32_dpp v83, v8, v76 quad_perm:[1,0,3,2] row_mask:0xf bank_mask:0xf bound_ctrl:1
	v_mul_f32_e32 v8, v8, v76
	v_cvt_pk_bf16_f32 v8, v8, v83
	v_mul_f32_dpp v83, v24, v76 quad_perm:[1,0,3,2] row_mask:0xf bank_mask:0xf bound_ctrl:1
	v_mul_f32_e32 v24, v24, v76
	v_cvt_pk_bf16_f32 v24, v24, v83
	v_mul_f32_dpp v83, v40, v76 quad_perm:[1,0,3,2] row_mask:0xf bank_mask:0xf bound_ctrl:1
	v_mul_f32_e32 v40, v40, v76
	v_cvt_pk_bf16_f32 v40, v40, v83
	v_mul_f32_dpp v83, v56, v76 quad_perm:[1,0,3,2] row_mask:0xf bank_mask:0xf bound_ctrl:1
	v_mul_f32_e32 v56, v56, v76
	v_cvt_pk_bf16_f32 v56, v56, v83
	v_mul_f32_dpp v83, v9, v77 quad_perm:[1,0,3,2] row_mask:0xf bank_mask:0xf bound_ctrl:1
	v_mul_f32_e32 v9, v9, v77
	v_cvt_pk_bf16_f32 v9, v9, v83
	v_mul_f32_dpp v83, v25, v77 quad_perm:[1,0,3,2] row_mask:0xf bank_mask:0xf bound_ctrl:1
	v_mul_f32_e32 v25, v25, v77
	v_cvt_pk_bf16_f32 v25, v25, v83
	v_mul_f32_dpp v83, v41, v77 quad_perm:[1,0,3,2] row_mask:0xf bank_mask:0xf bound_ctrl:1
	v_mul_f32_e32 v41, v41, v77
	v_cvt_pk_bf16_f32 v41, v41, v83
	v_mul_f32_dpp v83, v57, v77 quad_perm:[1,0,3,2] row_mask:0xf bank_mask:0xf bound_ctrl:1
	v_mul_f32_e32 v57, v57, v77
	v_cvt_pk_bf16_f32 v57, v57, v83
	v_mul_f32_dpp v83, v10, v70 quad_perm:[1,0,3,2] row_mask:0xf bank_mask:0xf bound_ctrl:1
	v_mul_f32_e32 v10, v10, v70
	v_cvt_pk_bf16_f32 v10, v10, v83
	v_mul_f32_dpp v83, v26, v70 quad_perm:[1,0,3,2] row_mask:0xf bank_mask:0xf bound_ctrl:1
	v_mul_f32_e32 v26, v26, v70
	v_cvt_pk_bf16_f32 v26, v26, v83
	v_mul_f32_dpp v83, v42, v70 quad_perm:[1,0,3,2] row_mask:0xf bank_mask:0xf bound_ctrl:1
	v_mul_f32_e32 v42, v42, v70
	v_cvt_pk_bf16_f32 v42, v42, v83
	v_mul_f32_dpp v83, v58, v70 quad_perm:[1,0,3,2] row_mask:0xf bank_mask:0xf bound_ctrl:1
	v_mul_f32_e32 v58, v58, v70
	v_cvt_pk_bf16_f32 v58, v58, v83
	v_mul_f32_dpp v83, v11, v71 quad_perm:[1,0,3,2] row_mask:0xf bank_mask:0xf bound_ctrl:1
	v_mul_f32_e32 v11, v11, v71
	v_cvt_pk_bf16_f32 v11, v11, v83
	v_mul_f32_dpp v83, v27, v71 quad_perm:[1,0,3,2] row_mask:0xf bank_mask:0xf bound_ctrl:1
	v_mul_f32_e32 v27, v27, v71
	v_cvt_pk_bf16_f32 v27, v27, v83
	v_mul_f32_dpp v83, v43, v71 quad_perm:[1,0,3,2] row_mask:0xf bank_mask:0xf bound_ctrl:1
	v_mul_f32_e32 v43, v43, v71
	v_cvt_pk_bf16_f32 v43, v43, v83
	v_mul_f32_dpp v83, v59, v71 quad_perm:[1,0,3,2] row_mask:0xf bank_mask:0xf bound_ctrl:1
	v_mul_f32_e32 v59, v59, v71
	v_cvt_pk_bf16_f32 v59, v59, v83
	v_mul_f32_dpp v83, v12, v72 quad_perm:[1,0,3,2] row_mask:0xf bank_mask:0xf bound_ctrl:1
	v_mul_f32_e32 v12, v12, v72
	v_cvt_pk_bf16_f32 v12, v12, v83
	v_mul_f32_dpp v83, v28, v72 quad_perm:[1,0,3,2] row_mask:0xf bank_mask:0xf bound_ctrl:1
	v_mul_f32_e32 v28, v28, v72
	v_cvt_pk_bf16_f32 v28, v28, v83
	v_mul_f32_dpp v83, v44, v72 quad_perm:[1,0,3,2] row_mask:0xf bank_mask:0xf bound_ctrl:1
	v_mul_f32_e32 v44, v44, v72
	v_cvt_pk_bf16_f32 v44, v44, v83
	v_mul_f32_dpp v83, v60, v72 quad_perm:[1,0,3,2] row_mask:0xf bank_mask:0xf bound_ctrl:1
	v_mul_f32_e32 v60, v60, v72
	v_cvt_pk_bf16_f32 v60, v60, v83
	v_mul_f32_dpp v83, v13, v73 quad_perm:[1,0,3,2] row_mask:0xf bank_mask:0xf bound_ctrl:1
	v_mul_f32_e32 v13, v13, v73
	v_cvt_pk_bf16_f32 v13, v13, v83
	v_mul_f32_dpp v83, v29, v73 quad_perm:[1,0,3,2] row_mask:0xf bank_mask:0xf bound_ctrl:1
	v_mul_f32_e32 v29, v29, v73
	v_cvt_pk_bf16_f32 v29, v29, v83
	v_mul_f32_dpp v83, v45, v73 quad_perm:[1,0,3,2] row_mask:0xf bank_mask:0xf bound_ctrl:1
	v_mul_f32_e32 v45, v45, v73
	v_cvt_pk_bf16_f32 v45, v45, v83
	v_mul_f32_dpp v83, v61, v73 quad_perm:[1,0,3,2] row_mask:0xf bank_mask:0xf bound_ctrl:1
	v_mul_f32_e32 v61, v61, v73
	v_cvt_pk_bf16_f32 v61, v61, v83
	v_mul_f32_dpp v83, v14, v66 quad_perm:[1,0,3,2] row_mask:0xf bank_mask:0xf bound_ctrl:1
	v_mul_f32_e32 v14, v14, v66
	v_cvt_pk_bf16_f32 v14, v14, v83
	v_mul_f32_dpp v83, v30, v66 quad_perm:[1,0,3,2] row_mask:0xf bank_mask:0xf bound_ctrl:1
	v_mul_f32_e32 v30, v30, v66
	v_cvt_pk_bf16_f32 v30, v30, v83
	v_mul_f32_dpp v83, v46, v66 quad_perm:[1,0,3,2] row_mask:0xf bank_mask:0xf bound_ctrl:1
	v_mul_f32_e32 v46, v46, v66
	v_cvt_pk_bf16_f32 v46, v46, v83
	v_mul_f32_dpp v83, v62, v66 quad_perm:[1,0,3,2] row_mask:0xf bank_mask:0xf bound_ctrl:1
	v_mul_f32_e32 v62, v62, v66
	v_cvt_pk_bf16_f32 v62, v62, v83
	v_mul_f32_dpp v83, v15, v67 quad_perm:[1,0,3,2] row_mask:0xf bank_mask:0xf bound_ctrl:1
	v_mul_f32_e32 v15, v15, v67
	v_cvt_pk_bf16_f32 v15, v15, v83
	v_mul_f32_dpp v83, v31, v67 quad_perm:[1,0,3,2] row_mask:0xf bank_mask:0xf bound_ctrl:1
	v_mul_f32_e32 v31, v31, v67
	v_cvt_pk_bf16_f32 v31, v31, v83
	v_mul_f32_dpp v83, v47, v67 quad_perm:[1,0,3,2] row_mask:0xf bank_mask:0xf bound_ctrl:1
	v_mul_f32_e32 v47, v47, v67
	v_cvt_pk_bf16_f32 v47, v47, v83
	v_mul_f32_dpp v83, v63, v67 quad_perm:[1,0,3,2] row_mask:0xf bank_mask:0xf bound_ctrl:1
	v_mul_f32_e32 v63, v63, v67
	v_cvt_pk_bf16_f32 v63, v63, v83
	v_mul_f32_dpp v83, v16, v68 quad_perm:[1,0,3,2] row_mask:0xf bank_mask:0xf bound_ctrl:1
	v_mul_f32_e32 v16, v16, v68
	v_cvt_pk_bf16_f32 v16, v16, v83
	v_mul_f32_dpp v83, v32, v68 quad_perm:[1,0,3,2] row_mask:0xf bank_mask:0xf bound_ctrl:1
	v_mul_f32_e32 v32, v32, v68
	v_cvt_pk_bf16_f32 v32, v32, v83
	v_mul_f32_dpp v83, v48, v68 quad_perm:[1,0,3,2] row_mask:0xf bank_mask:0xf bound_ctrl:1
	v_mul_f32_e32 v48, v48, v68
	v_cvt_pk_bf16_f32 v48, v48, v83
	v_mul_f32_dpp v83, v64, v68 quad_perm:[1,0,3,2] row_mask:0xf bank_mask:0xf bound_ctrl:1
	v_mul_f32_e32 v64, v64, v68
	v_cvt_pk_bf16_f32 v64, v64, v83
	v_mul_f32_dpp v83, v17, v69 quad_perm:[1,0,3,2] row_mask:0xf bank_mask:0xf bound_ctrl:1
	v_mul_f32_e32 v17, v17, v69
	v_cvt_pk_bf16_f32 v17, v17, v83
	v_mul_f32_dpp v83, v33, v69 quad_perm:[1,0,3,2] row_mask:0xf bank_mask:0xf bound_ctrl:1
	v_mul_f32_e32 v33, v33, v69
	v_cvt_pk_bf16_f32 v33, v33, v83
	v_mul_f32_dpp v83, v49, v69 quad_perm:[1,0,3,2] row_mask:0xf bank_mask:0xf bound_ctrl:1
	v_mul_f32_e32 v49, v49, v69
	v_cvt_pk_bf16_f32 v49, v49, v83
	v_mul_f32_dpp v83, v65, v69 quad_perm:[1,0,3,2] row_mask:0xf bank_mask:0xf bound_ctrl:1
	v_mul_f32_e32 v65, v65, v69
	v_cvt_pk_bf16_f32 v65, v65, v83
	s_and_saveexec_b64 s[4:5], vcc
	ds_write_b32 v78, v2
	ds_write_b32 v78, v18 offset:64
	ds_write_b32 v78, v34 offset:128
	ds_write_b32 v78, v50 offset:192
	ds_write_b32 v78, v3 offset:256
	ds_write_b32 v78, v19 offset:320
	ds_write_b32 v78, v35 offset:384
	ds_write_b32 v78, v51 offset:448
	ds_write_b32 v78, v4 offset:512
	ds_write_b32 v78, v20 offset:576
	ds_write_b32 v78, v36 offset:640
	ds_write_b32 v78, v52 offset:704
	ds_write_b32 v78, v5 offset:768
	ds_write_b32 v78, v21 offset:832
	ds_write_b32 v78, v37 offset:896
	ds_write_b32 v78, v53 offset:960
	ds_write_b32 v78, v6 offset:2048
	ds_write_b32 v78, v22 offset:2112
	ds_write_b32 v78, v38 offset:2176
	ds_write_b32 v78, v54 offset:2240
	ds_write_b32 v78, v7 offset:2304
	ds_write_b32 v78, v23 offset:2368
	ds_write_b32 v78, v39 offset:2432
	ds_write_b32 v78, v55 offset:2496
	ds_write_b32 v78, v8 offset:2560
	ds_write_b32 v78, v24 offset:2624
	ds_write_b32 v78, v40 offset:2688
	ds_write_b32 v78, v56 offset:2752
	ds_write_b32 v78, v9 offset:2816
	ds_write_b32 v78, v25 offset:2880
	ds_write_b32 v78, v41 offset:2944
	ds_write_b32 v78, v57 offset:3008
	ds_write_b32 v78, v10 offset:4096
	ds_write_b32 v78, v26 offset:4160
	ds_write_b32 v78, v42 offset:4224
	ds_write_b32 v78, v58 offset:4288
	ds_write_b32 v78, v11 offset:4352
	ds_write_b32 v78, v27 offset:4416
	ds_write_b32 v78, v43 offset:4480
	ds_write_b32 v78, v59 offset:4544
	ds_write_b32 v78, v12 offset:4608
	ds_write_b32 v78, v28 offset:4672
	ds_write_b32 v78, v44 offset:4736
	ds_write_b32 v78, v60 offset:4800
	ds_write_b32 v78, v13 offset:4864
	ds_write_b32 v78, v29 offset:4928
	ds_write_b32 v78, v45 offset:4992
	ds_write_b32 v78, v61 offset:5056
	ds_write_b32 v78, v14 offset:6144
	ds_write_b32 v78, v30 offset:6208
	ds_write_b32 v78, v46 offset:6272
	ds_write_b32 v78, v62 offset:6336
	ds_write_b32 v78, v15 offset:6400
	ds_write_b32 v78, v31 offset:6464
	ds_write_b32 v78, v47 offset:6528
	ds_write_b32 v78, v63 offset:6592
	ds_write_b32 v78, v16 offset:6656
	ds_write_b32 v78, v32 offset:6720
	ds_write_b32 v78, v48 offset:6784
	ds_write_b32 v78, v64 offset:6848
	ds_write_b32 v78, v17 offset:6912
	ds_write_b32 v78, v33 offset:6976
	ds_write_b32 v78, v49 offset:7040
	ds_write_b32 v78, v65 offset:7104
	s_branch .LBB0_1413
